# attention QK loop head rewritten (batched bias ds_reads + prefetched K fragments); P_br epilogue first gate load overlapped with the rest
# speedup vs baseline: 1.0255x; 1.0255x over previous
; #define LAS __attribute__((address_space(3)))
; #define MFMA32(a, b, c) __builtin_amdgcn_mfma_f32_32x32x16_bf16((a), (b), (c), 0, 0, 0)
; __device__ __forceinline__ void attn_item(const bf16_t* __restrict__ Q, const bf16_t* __restrict__ Kb, const bf16_t* __restrict__ VT, const bf16_t* __restrict__ GA, ...
;     ...
;     for (int j = jmin; j <= 8; ++j) {
;         const LAS unsigned char* kfp = pl + buf * ATT_WAVE_LDS + pr * ATP + 16 * hh;
;         const LAS unsigned char* vfp = pl + buf * ATT_WAVE_LDS + 64 * ATP + r * ATP + 16 * hh;
;         f32x16 s0, s1;
;         if (j <= 3) {
;             const bf16x8 k0 = *(const LAS bf16x8*)(kfp), k1 = *(const LAS bf16x8*)(kfp + 32 * ATP);
;             s0 = MFMA32(k0, qf[0], cinit); s1 = MFMA32(k1, qf[0], cinit);
;         } else {
;             const LAS float* bp = btab + (qloc + 64 * (8 - j) + 63 - 8 * hh);
; #pragma unroll
;             for (int i = 0; i < 16; ++i) {
;                 const int key = (i & 3) + 4 * ((i >> 2) & 1) + 16 * (i >> 3);
;                 s0[i] = bp[-key] - mref; s1[i] = bp[-key - 32] - mref;
;             }
;             const bf16x8 k0 = *(const LAS bf16x8*)(kfp), k1 = *(const LAS bf16x8*)(kfp + 32 * ATP);
;             s0 = MFMA32(k0, qf[0], s0); s1 = MFMA32(k1, qf[0], s1);
;         }
; #pragma unroll
;         for (int d0 = 1; d0 < 4; ++d0) {
;             const bf16x8 k0 = *(const LAS bf16x8*)(kfp + d0 * 32), k1 = *(const LAS bf16x8*)(kfp + 32 * ATP + d0 * 32);
;             s0 = MFMA32(k0, qf[d0], s0); s1 = MFMA32(k1, qf[d0], s1);
;         }
.LBB0_255:
	s_mul_i32 s7, s72, 0x4800
	s_add_i32 s28, s77, s7
	s_cmp_gt_i32 s33, 2
	v_add3_u32 v189, s28, v166, v167
	s_cbranch_scc0 .Latt0_nobias
	ds_read2_b32 v[50:51], v188 offset0:55 offset1:54
	ds_read2_b32 v[52:53], v188 offset0:53 offset1:52
	ds_read2_b32 v[54:55], v188 offset0:51 offset1:50
	ds_read2_b32 v[56:57], v188 offset0:49 offset1:48
	ds_read2_b32 v[58:59], v188 offset0:39 offset1:38
	ds_read2_b32 v[60:61], v188 offset0:37 offset1:36
	ds_read2_b32 v[62:63], v188 offset0:35 offset1:34
	ds_read2_b32 v[64:65], v188 offset0:33 offset1:32
	ds_read2_b32 v[66:67], v188 offset0:23 offset1:22
	ds_read2_b32 v[68:69], v188 offset0:21 offset1:20
	ds_read2_b32 v[70:71], v188 offset0:19 offset1:18
	ds_read2_b32 v[72:73], v188 offset0:17 offset1:16
	ds_read2_b32 v[74:75], v188 offset0:7 offset1:6
	ds_read2_b32 v[76:77], v188 offset0:5 offset1:4
	ds_read2_b32 v[78:79], v188 offset0:3 offset1:2
	ds_read2_b32 v[80:81], v188 offset0:1
	ds_read_b128 v[190:193], v189
	ds_read_b128 v[194:197], v189 offset:4608
	ds_read_b128 v[198:201], v189 offset:32
	ds_read_b128 v[202:205], v189 offset:4640
	ds_read_b128 v[206:209], v189 offset:64
	ds_read_b128 v[210:213], v189 offset:4672
	ds_read_b128 v[218:221], v189 offset:4704
	ds_read_b128 v[222:225], v189 offset:96
	s_waitcnt lgkmcnt(8)
	v_pk_add_f32 v[50:51], v[50:51], v[132:133] op_sel_hi:[1,0] neg_lo:[0,1] neg_hi:[0,1]
	v_pk_add_f32 v[52:53], v[52:53], v[132:133] op_sel_hi:[1,0] neg_lo:[0,1] neg_hi:[0,1]
	v_pk_add_f32 v[54:55], v[54:55], v[132:133] op_sel_hi:[1,0] neg_lo:[0,1] neg_hi:[0,1]
	v_pk_add_f32 v[56:57], v[56:57], v[132:133] op_sel_hi:[1,0] neg_lo:[0,1] neg_hi:[0,1]
	v_pk_add_f32 v[58:59], v[58:59], v[132:133] op_sel_hi:[1,0] neg_lo:[0,1] neg_hi:[0,1]
	v_pk_add_f32 v[60:61], v[60:61], v[132:133] op_sel_hi:[1,0] neg_lo:[0,1] neg_hi:[0,1]
	v_pk_add_f32 v[62:63], v[62:63], v[132:133] op_sel_hi:[1,0] neg_lo:[0,1] neg_hi:[0,1]
	v_pk_add_f32 v[64:65], v[64:65], v[132:133] op_sel_hi:[1,0] neg_lo:[0,1] neg_hi:[0,1]
	v_pk_add_f32 v[66:67], v[66:67], v[132:133] op_sel_hi:[1,0] neg_lo:[0,1] neg_hi:[0,1]
	v_pk_add_f32 v[68:69], v[68:69], v[132:133] op_sel_hi:[1,0] neg_lo:[0,1] neg_hi:[0,1]
	v_pk_add_f32 v[70:71], v[70:71], v[132:133] op_sel_hi:[1,0] neg_lo:[0,1] neg_hi:[0,1]
	v_pk_add_f32 v[72:73], v[72:73], v[132:133] op_sel_hi:[1,0] neg_lo:[0,1] neg_hi:[0,1]
	v_pk_add_f32 v[74:75], v[74:75], v[132:133] op_sel_hi:[1,0] neg_lo:[0,1] neg_hi:[0,1]
	v_pk_add_f32 v[76:77], v[76:77], v[132:133] op_sel_hi:[1,0] neg_lo:[0,1] neg_hi:[0,1]
	v_pk_add_f32 v[78:79], v[78:79], v[132:133] op_sel_hi:[1,0] neg_lo:[0,1] neg_hi:[0,1]
	v_pk_add_f32 v[80:81], v[80:81], v[132:133] op_sel_hi:[1,0] neg_lo:[0,1] neg_hi:[0,1]
	s_waitcnt lgkmcnt(7)
	v_mfma_f32_32x32x16_bf16 v[50:65], v[190:193], v[82:85], v[50:65]
	s_waitcnt lgkmcnt(6)
	v_mfma_f32_32x32x16_bf16 v[66:81], v[194:197], v[82:85], v[66:81]
	s_branch .Latt0_qkrest
.Latt0_nobias:
	ds_read_b128 v[190:193], v189
	ds_read_b128 v[194:197], v189 offset:4608
	ds_read_b128 v[198:201], v189 offset:32
	ds_read_b128 v[202:205], v189 offset:4640
	ds_read_b128 v[206:209], v189 offset:64
	ds_read_b128 v[210:213], v189 offset:4672
	ds_read_b128 v[218:221], v189 offset:4704
	ds_read_b128 v[222:225], v189 offset:96
	s_waitcnt lgkmcnt(7)
	v_mfma_f32_32x32x16_bf16 v[50:65], v[190:193], v[82:85], v[34:49]
	s_waitcnt lgkmcnt(6)
	v_mfma_f32_32x32x16_bf16 v[66:81], v[194:197], v[82:85], v[34:49]
; #define LAS __attribute__((address_space(3)))
; #define MFMA32(a, b, c) __builtin_amdgcn_mfma_f32_32x32x16_bf16((a), (b), (c), 0, 0, 0)
; __device__ __forceinline__ void attn_item(const bf16_t* __restrict__ Q, const bf16_t* __restrict__ Kb, const bf16_t* __restrict__ VT, const bf16_t* __restrict__ GA, ...
;     ...
;         for (int d0 = 1; d0 < 4; ++d0) {
;             const bf16x8 k0 = *(const LAS bf16x8*)(kfp + d0 * 32), k1 = *(const LAS bf16x8*)(kfp + 32 * ATP + d0 * 32);
;             s0 = MFMA32(k0, qf[d0], s0); s1 = MFMA32(k1, qf[d0], s1);
;         }
;         float tmax = fmaxf(s0[0], s1[0]);
; #pragma unroll
;         for (int i = 1; i < 16; ++i) tmax = fmaxf(tmax, fmaxf(s0[i], s1[i]));
;         tmax = fmaxf(tmax, __shfl_xor(tmax, 32));
;         if (j == jmin || __any(tmax > ATT_THR)) {
;             const float dl = (j == jmin) ? tmax : fmaxf(tmax, 0.f);
;             mref += dl;
;             const float alpha = (j == jmin) ? 1.f : __builtin_amdgcn_exp2f(-dl);
;             lrun *= alpha;
; #pragma unroll
;             for (int i = 0; i < 16; ++i) { s0[i] -= dl; s1[i] -= dl; o0[i] *= alpha; o1[i] *= alpha; cinit[i] = cfar - mref; }
.Latt0_qkrest:
	s_waitcnt lgkmcnt(5)
	v_mfma_f32_32x32x16_bf16 v[50:65], v[198:201], v[86:89], v[50:65]
	s_waitcnt lgkmcnt(4)
	v_mfma_f32_32x32x16_bf16 v[66:81], v[202:205], v[86:89], v[66:81]
	s_waitcnt lgkmcnt(3)
	v_mfma_f32_32x32x16_bf16 v[50:65], v[206:209], v[90:93], v[50:65]
	s_waitcnt lgkmcnt(2)
	v_mfma_f32_32x32x16_bf16 v[66:81], v[210:213], v[90:93], v[66:81]
	s_waitcnt lgkmcnt(1)
	v_mfma_f32_32x32x16_bf16 v[66:81], v[218:221], v[94:97], v[66:81]
	s_waitcnt lgkmcnt(0)
	v_mfma_f32_32x32x16_bf16 v[50:65], v[222:225], v[94:97], v[50:65]
	s_nop 9
	v_max_f32_e32 v189, v67, v67
	s_nop 1
	v_max_f32_e32 v190, v51, v51
	v_max_f32_e32 v189, v190, v189
	v_max_f32_e32 v190, v68, v68
	v_max_f32_e32 v191, v52, v52
	v_max_f32_e32 v190, v191, v190
	v_max_f32_e32 v191, v69, v69
	v_max_f32_e32 v192, v53, v53
	v_max3_f32 v189, v50, v66, v189
	v_max_f32_e32 v191, v192, v191
	v_max3_f32 v189, v189, v190, v191
	v_max_f32_e32 v190, v70, v70
	v_max_f32_e32 v191, v54, v54
	v_max_f32_e32 v190, v191, v190
	v_max_f32_e32 v191, v71, v71
	v_max_f32_e32 v192, v55, v55
	v_max_f32_e32 v191, v192, v191
	v_max3_f32 v189, v189, v190, v191
	v_max_f32_e32 v190, v72, v72
	v_max_f32_e32 v191, v56, v56
	v_max_f32_e32 v190, v191, v190
	v_max_f32_e32 v191, v73, v73
	v_max_f32_e32 v192, v57, v57
	v_max_f32_e32 v191, v192, v191
	v_max3_f32 v189, v189, v190, v191
	v_max_f32_e32 v190, v74, v74
	v_max_f32_e32 v191, v58, v58
	v_max_f32_e32 v190, v191, v190
	v_max_f32_e32 v191, v75, v75
	v_max_f32_e32 v192, v59, v59
	v_max_f32_e32 v191, v192, v191
	v_max3_f32 v189, v189, v190, v191
	v_max_f32_e32 v190, v76, v76
	v_max_f32_e32 v191, v60, v60
	v_max_f32_e32 v190, v191, v190
	v_max_f32_e32 v191, v77, v77
	v_max_f32_e32 v192, v61, v61
	v_max_f32_e32 v191, v192, v191
	v_max3_f32 v189, v189, v190, v191
	v_max_f32_e32 v190, v78, v78
	v_max_f32_e32 v191, v62, v62
	v_max_f32_e32 v190, v191, v190
	v_max_f32_e32 v191, v79, v79
	v_max_f32_e32 v192, v63, v63
	v_max_f32_e32 v191, v192, v191
	v_max3_f32 v189, v189, v190, v191
	v_max_f32_e32 v190, v80, v80
	v_max_f32_e32 v191, v64, v64
	v_max_f32_e32 v190, v191, v190
	v_max_f32_e32 v191, v81, v81
	v_max_f32_e32 v192, v65, v65
	v_max_f32_e32 v191, v192, v191
	v_max3_f32 v189, v189, v190, v191
	ds_bpermute_b32 v190, v1, v189
	s_waitcnt lgkmcnt(0)
	v_max_f32_e32 v190, v190, v190
	v_max_f32_e32 v189, v189, v190
	v_cmp_lt_f32_e32 vcc, s94, v189
	s_cbranch_vccz .LBB0_261
	v_max_f32_e32 v34, v189, v189
	v_max_f32_e32 v36, 0, v34
	v_exp_f32_e64 v38, -v36
	v_add_f32_e32 v132, v132, v36
	v_sub_f32_e32 v34, v0, v132
	v_pk_add_f32 v[50:51], v[50:51], v[36:37] op_sel_hi:[1,0] neg_lo:[0,1] neg_hi:[0,1]
	v_pk_add_f32 v[66:67], v[66:67], v[36:37] op_sel_hi:[1,0] neg_lo:[0,1] neg_hi:[0,1]
	v_pk_add_f32 v[52:53], v[52:53], v[36:37] op_sel_hi:[1,0] neg_lo:[0,1] neg_hi:[0,1]
	v_pk_add_f32 v[68:69], v[68:69], v[36:37] op_sel_hi:[1,0] neg_lo:[0,1] neg_hi:[0,1]
	v_pk_add_f32 v[54:55], v[54:55], v[36:37] op_sel_hi:[1,0] neg_lo:[0,1] neg_hi:[0,1]
	v_pk_add_f32 v[70:71], v[70:71], v[36:37] op_sel_hi:[1,0] neg_lo:[0,1] neg_hi:[0,1]
	v_pk_add_f32 v[56:57], v[56:57], v[36:37] op_sel_hi:[1,0] neg_lo:[0,1] neg_hi:[0,1]
	v_pk_add_f32 v[72:73], v[72:73], v[36:37] op_sel_hi:[1,0] neg_lo:[0,1] neg_hi:[0,1]
	v_pk_add_f32 v[58:59], v[58:59], v[36:37] op_sel_hi:[1,0] neg_lo:[0,1] neg_hi:[0,1]
	v_pk_add_f32 v[74:75], v[74:75], v[36:37] op_sel_hi:[1,0] neg_lo:[0,1] neg_hi:[0,1]
	v_pk_add_f32 v[60:61], v[60:61], v[36:37] op_sel_hi:[1,0] neg_lo:[0,1] neg_hi:[0,1]
	v_pk_add_f32 v[76:77], v[76:77], v[36:37] op_sel_hi:[1,0] neg_lo:[0,1] neg_hi:[0,1]
	v_pk_add_f32 v[62:63], v[62:63], v[36:37] op_sel_hi:[1,0] neg_lo:[0,1] neg_hi:[0,1]
	v_pk_add_f32 v[78:79], v[78:79], v[36:37] op_sel_hi:[1,0] neg_lo:[0,1] neg_hi:[0,1]
	v_pk_add_f32 v[64:65], v[64:65], v[36:37] op_sel_hi:[1,0] neg_lo:[0,1] neg_hi:[0,1]
	v_pk_add_f32 v[80:81], v[80:81], v[36:37] op_sel_hi:[1,0] neg_lo:[0,1] neg_hi:[0,1]
	v_pk_mul_f32 v[16:17], v[16:17], v[38:39] op_sel_hi:[1,0]
	v_pk_mul_f32 v[14:15], v[14:15], v[38:39] op_sel_hi:[1,0]
	v_pk_mul_f32 v[12:13], v[12:13], v[38:39] op_sel_hi:[1,0]
	v_pk_mul_f32 v[10:11], v[10:11], v[38:39] op_sel_hi:[1,0]
	v_pk_mul_f32 v[8:9], v[8:9], v[38:39] op_sel_hi:[1,0]
	v_pk_mul_f32 v[6:7], v[6:7], v[38:39] op_sel_hi:[1,0]
	v_pk_mul_f32 v[4:5], v[4:5], v[38:39] op_sel_hi:[1,0]
	v_pk_mul_f32 v[2:3], v[2:3], v[38:39] op_sel_hi:[1,0]
	v_pk_mul_f32 v[32:33], v[32:33], v[38:39] op_sel_hi:[1,0]
	v_pk_mul_f32 v[30:31], v[30:31], v[38:39] op_sel_hi:[1,0]
	v_pk_mul_f32 v[28:29], v[28:29], v[38:39] op_sel_hi:[1,0]
	v_pk_mul_f32 v[26:27], v[26:27], v[38:39] op_sel_hi:[1,0]
	v_pk_mul_f32 v[24:25], v[24:25], v[38:39] op_sel_hi:[1,0]
	v_pk_mul_f32 v[22:23], v[22:23], v[38:39] op_sel_hi:[1,0]
	v_pk_mul_f32 v[20:21], v[20:21], v[38:39] op_sel_hi:[1,0]
	v_pk_mul_f32 v[18:19], v[18:19], v[38:39] op_sel_hi:[1,0]
	v_mul_f32_e32 v187, v187, v38
	v_mov_b32_e32 v35, v34
	v_mov_b32_e32 v36, v34
	v_mov_b32_e32 v37, v34
	v_mov_b32_e32 v38, v34
	v_mov_b32_e32 v39, v34
	v_mov_b32_e32 v40, v34
	v_mov_b32_e32 v41, v34
	v_mov_b32_e32 v42, v34
	v_mov_b32_e32 v43, v34
	v_mov_b32_e32 v44, v34
	v_mov_b32_e32 v45, v34
	v_mov_b32_e32 v46, v34
	v_mov_b32_e32 v47, v34
	v_mov_b32_e32 v48, v34
	v_mov_b32_e32 v49, v34

;     __device__ __forceinline__ void operator()(f32x4 (&acc)[2][2][4][2], const Unit& u, int wr, int wc, int fr, int fq) const {
;         const int row0 = u.pm * BM + wr * 64 + fr, col0 = u.pn * BM + wc * 32 + 8 * fq;
;         const int z = u.z;
;         const bf16_t* gz = gates + (size_t)row0 * (3 * DM) + z * DM + col0;
;         if (z < 2) {
; #pragma unroll
;             for (int ai = 0; ai < 2; ++ai) {
;                 u32x4 gn[4][2], gd[4][2];
; #pragma unroll
;                 for (int m = 0; m < 4; ++m)
; #pragma unroll
;                     for (int bj = 0; bj < 2; ++bj) { const bf16_t* p = gz + (size_t)(ai * HALF + m * 16) * (3 * DM) + bj * HALF; gn[m][bj] = *(const u32x4*)p; gd[m][bj] = *(const u32x4*)(p + DM); }
.LBB0_334:
	v_lshl_add_u32 v150, s4, 8, v178
	v_mov_b64_e32 v[130:131], s[12:13]
	v_lshl_or_b32 v128, s5, 8, v180
	v_mad_i64_i32 v[130:131], s[4:5], v150, s63, v[130:131]
	s_lshl_b32 s4, s82, 11
	s_ashr_i32 s5, s4, 31
	v_lshl_add_u64 v[130:131], s[4:5], 1, v[130:131]
	v_ashrrev_i32_e32 v129, 31, v128
	v_lshl_add_u64 v[176:177], v[128:129], 1, v[130:131]
	global_load_dwordx4 v[230:233], v[176:177], off
	s_mov_b64 s[4:5], -1
	s_cmp_gt_i32 s82, 1
	s_cbranch_scc1 .LBB0_337
	s_andn2_b64 vcc, exec, s[4:5]
	s_cbranch_vccz .LBB0_338

; __device__ __forceinline__ unsigned pk2(float lo, float hi) { f32x2 v = {lo, hi}; bf16x2_t b = __builtin_convertvector(v, bf16x2_t); return __builtin_bit_cast(unsigned, b); }
; __device__ __forceinline__ float bflo(unsigned u) { return __uint_as_float(u << 16); }
; __device__ __forceinline__ float bfhi(unsigned u) { return __uint_as_float(u & 0xffff0000u); }
;     __device__ __forceinline__ void operator()(f32x4 (&acc)[2][2][4][2], const Unit& u, int wr, int wc, int fr, int fq) const {
;     ...
; #pragma unroll
;             for (int ai = 0; ai < 2; ++ai) {
;                 u32x4 gn[4][2];
; #pragma unroll
;                 for (int m = 0; m < 4; ++m)
; #pragma unroll
;                     for (int bj = 0; bj < 2; ++bj) gn[m][bj] = *(const u32x4*)(gz + (size_t)(ai * HALF + m * 16) * (3 * DM) + bj * HALF);
; #pragma unroll
;                 for (int m = 0; m < 4; ++m)
; #pragma unroll
;                     for (int bj = 0; bj < 2; ++bj) {
;                         const u32x4 a = gn[m][bj];
;                         const f32x4 v0 = acc[ai][bj][m][0], v1 = acc[ai][bj][m][1];
;                         u32x4 w; w.x = pk2(v0[0] * __builtin_amdgcn_rcpf(bflo(a.x)), v0[1] * __builtin_amdgcn_rcpf(bfhi(a.x))); w.y = pk2(v0[2] * __builtin_amdgcn_rcpf(bflo(a.y)), v0[3] * __builtin_amdgcn_rcpf(bfhi(a.y)));
;                         w.z = pk2(v1[0] * __builtin_amdgcn_rcpf(bflo(a.z)), v1[1] * __builtin_amdgcn_rcpf(bfhi(a.z))); w.w = pk2(v1[2] * __builtin_amdgcn_rcpf(bflo(a.w)), v1[3] * __builtin_amdgcn_rcpf(bfhi(a.w)));
;                         *(u32x4*)(out + (size_t)(row0 + ai * HALF + m * 16) * DM + col0 + bj * HALF) = w;
;                     }
.LBB0_337:
	v_add_co_u32_e32 v130, vcc, 0x30000, v176
	global_load_dwordx4 v[144:147], v[176:177], off offset:256
	s_nop 0
	v_addc_co_u32_e32 v131, vcc, 0, v177, vcc
	global_load_dwordx4 v[186:189], v[130:131], off
	global_load_dwordx4 v[136:139], v[130:131], off offset:256
	v_add_co_u32_e32 v130, vcc, 0x60000, v176
	v_ashrrev_i32_e32 v151, 31, v150
	s_nop 0
	v_addc_co_u32_e32 v131, vcc, 0, v177, vcc
	global_load_dwordx4 v[190:193], v[130:131], off
	v_lshlrev_b64 v[152:153], 1, v[128:129]
	v_or_b32_e32 v128, 16, v150
	v_lshlrev_b64 v[132:133], 12, v[150:151]
	v_ashrrev_i32_e32 v129, 31, v128
	v_add_co_u32_e32 v200, vcc, 0x90000, v176
	v_lshl_add_u64 v[132:133], s[14:15], 0, v[132:133]
	v_lshlrev_b64 v[202:203], 12, v[128:129]
	v_addc_co_u32_e32 v201, vcc, 0, v177, vcc
	v_lshl_add_u64 v[148:149], v[132:133], 0, v[152:153]
	global_load_dwordx4 v[132:135], v[130:131], off offset:256
	global_load_dwordx4 v[140:143], v[200:201], off
	s_nop 0
	global_load_dwordx4 v[128:131], v[200:201], off offset:256
	s_waitcnt vmcnt(7)
	v_lshlrev_b32_e32 v184, 16, v230
	v_and_b32_e32 v185, 0xffff0000, v230
	v_lshlrev_b32_e32 v182, 16, v231
	v_and_b32_e32 v183, 0xffff0000, v231
	v_lshlrev_b32_e32 v158, 16, v232
	v_and_b32_e32 v159, 0xffff0000, v232
	v_lshlrev_b32_e32 v156, 16, v233
	v_and_b32_e32 v157, 0xffff0000, v233
	v_rcp_f32_e32 v154, v184
	v_rcp_f32_e32 v155, v185
	v_rcp_f32_e32 v194, v182
	v_rcp_f32_e32 v195, v183
	v_rcp_f32_e32 v196, v158
	v_rcp_f32_e32 v197, v159
	v_rcp_f32_e32 v198, v156
	v_rcp_f32_e32 v199, v157
	v_pk_mul_f32 v[154:155], v[124:125], v[154:155]
	v_pk_mul_f32 v[200:201], v[126:127], v[194:195]
	v_pk_mul_f32 v[196:197], v[120:121], v[196:197]
	v_pk_mul_f32 v[198:199], v[122:123], v[198:199]
	v_cvt_pk_bf16_f32 v194, v154, v155
	v_cvt_pk_bf16_f32 v195, v200, v201
	v_cvt_pk_bf16_f32 v196, v196, v197
	v_cvt_pk_bf16_f32 v197, v198, v199
	global_store_dwordx4 v[148:149], v[194:197], off
	s_waitcnt vmcnt(7)
	v_lshlrev_b32_e32 v151, 16, v144
	v_and_b32_e32 v154, 0xffff0000, v144
	v_lshlrev_b32_e32 v155, 16, v145
	v_and_b32_e32 v194, 0xffff0000, v145
	v_lshlrev_b32_e32 v195, 16, v146
	v_and_b32_e32 v196, 0xffff0000, v146
	v_lshlrev_b32_e32 v197, 16, v147
	v_and_b32_e32 v198, 0xffff0000, v147
	v_rcp_f32_e32 v144, v151
	v_rcp_f32_e32 v145, v154
	v_rcp_f32_e32 v146, v155
	v_rcp_f32_e32 v147, v194
	v_rcp_f32_e32 v154, v195
	v_rcp_f32_e32 v155, v196
	s_waitcnt vmcnt(6)
	v_lshlrev_b32_e32 v151, 16, v186
	v_and_b32_e32 v196, 0xffff0000, v186
	v_rcp_f32_e32 v194, v197
	v_rcp_f32_e32 v195, v198
	v_lshlrev_b32_e32 v197, 16, v187
	v_and_b32_e32 v198, 0xffff0000, v187
	v_lshlrev_b32_e32 v199, 16, v188
	v_and_b32_e32 v200, 0xffff0000, v188
	v_rcp_f32_e32 v186, v151
	v_rcp_f32_e32 v187, v196
	v_lshlrev_b32_e32 v201, 16, v189
	v_and_b32_e32 v204, 0xffff0000, v189
	v_rcp_f32_e32 v188, v197
	v_rcp_f32_e32 v189, v198
	v_rcp_f32_e32 v196, v199
	v_rcp_f32_e32 v197, v200
	v_rcp_f32_e32 v198, v201
	v_rcp_f32_e32 v199, v204
	v_pk_mul_f32 v[144:145], v[92:93], v[144:145]
	v_pk_mul_f32 v[146:147], v[94:95], v[146:147]
	v_pk_mul_f32 v[154:155], v[88:89], v[154:155]
	v_cvt_pk_bf16_f32 v144, v144, v145
	v_cvt_pk_bf16_f32 v145, v146, v147
	v_cvt_pk_bf16_f32 v146, v154, v155
	v_pk_mul_f32 v[154:155], v[116:117], v[186:187]
	v_pk_mul_f32 v[188:189], v[118:119], v[188:189]
	v_cvt_pk_bf16_f32 v186, v154, v155
	v_pk_mul_f32 v[154:155], v[112:113], v[196:197]
	v_cvt_pk_bf16_f32 v187, v188, v189
	v_cvt_pk_bf16_f32 v188, v154, v155
	v_pk_mul_f32 v[154:155], v[114:115], v[198:199]
	v_pk_mul_f32 v[194:195], v[90:91], v[194:195]
	v_cvt_pk_bf16_f32 v189, v154, v155
	v_lshl_add_u64 v[154:155], s[14:15], 0, v[202:203]
	s_waitcnt vmcnt(5)
	v_lshlrev_b32_e32 v151, 16, v136
	v_cvt_pk_bf16_f32 v147, v194, v195
	v_lshl_add_u64 v[154:155], v[154:155], 0, v[152:153]
	v_rcp_f32_e32 v194, v151
	s_waitcnt vmcnt(4)
	v_lshlrev_b32_e32 v151, 16, v190
	global_store_dwordx4 v[154:155], v[186:189], off
	v_and_b32_e32 v136, 0xffff0000, v136
	v_rcp_f32_e32 v195, v136
	v_rcp_f32_e32 v186, v151
	v_and_b32_e32 v151, 0xffff0000, v190
	v_rcp_f32_e32 v187, v151
	v_lshlrev_b32_e32 v151, 16, v191
	v_rcp_f32_e32 v188, v151
	v_and_b32_e32 v151, 0xffff0000, v191
	v_rcp_f32_e32 v189, v151
	v_lshlrev_b32_e32 v151, 16, v192
	v_rcp_f32_e32 v190, v151
	v_and_b32_e32 v151, 0xffff0000, v192
	v_rcp_f32_e32 v191, v151
	v_lshlrev_b32_e32 v151, 16, v193
	v_lshlrev_b32_e32 v136, 16, v137
	v_rcp_f32_e32 v192, v151
	v_and_b32_e32 v151, 0xffff0000, v193
	v_rcp_f32_e32 v196, v136
	v_and_b32_e32 v136, 0xffff0000, v137
	v_rcp_f32_e32 v193, v151
	v_rcp_f32_e32 v197, v136
	v_or_b32_e32 v136, 32, v150
	v_ashrrev_i32_e32 v137, 31, v136
	v_lshlrev_b64 v[136:137], 12, v[136:137]
	v_pk_mul_f32 v[186:187], v[108:109], v[186:187]
	v_pk_mul_f32 v[188:189], v[110:111], v[188:189]
	v_cvt_pk_bf16_f32 v186, v186, v187
	v_cvt_pk_bf16_f32 v187, v188, v189
	v_pk_mul_f32 v[188:189], v[104:105], v[190:191]
	v_pk_mul_f32 v[190:191], v[106:107], v[192:193]
	v_lshl_add_u64 v[136:137], s[14:15], 0, v[136:137]
	v_cvt_pk_bf16_f32 v188, v188, v189
	v_cvt_pk_bf16_f32 v189, v190, v191
	v_lshl_add_u64 v[190:191], v[136:137], 0, v[152:153]
	v_or_b32_e32 v136, 48, v150
	s_waitcnt vmcnt(3)
; __device__ __forceinline__ unsigned pk2(float lo, float hi) { f32x2 v = {lo, hi}; bf16x2_t b = __builtin_convertvector(v, bf16x2_t); return __builtin_bit_cast(unsigned, b); }
; __device__ __forceinline__ float bflo(unsigned u) { return __uint_as_float(u << 16); }
; __device__ __forceinline__ float bfhi(unsigned u) { return __uint_as_float(u & 0xffff0000u); }
;     __device__ __forceinline__ void operator()(f32x4 (&acc)[2][2][4][2], const Unit& u, int wr, int wc, int fr, int fq) const {
;     ...
; #pragma unroll
;             for (int ai = 0; ai < 2; ++ai) {
;                 u32x4 gn[4][2];
; #pragma unroll
;                 for (int m = 0; m < 4; ++m)
; #pragma unroll
;                     for (int bj = 0; bj < 2; ++bj) gn[m][bj] = *(const u32x4*)(gz + (size_t)(ai * HALF + m * 16) * (3 * DM) + bj * HALF);
; #pragma unroll
;                 for (int m = 0; m < 4; ++m)
; #pragma unroll
;                     for (int bj = 0; bj < 2; ++bj) {
;                         const u32x4 a = gn[m][bj];
;                         const f32x4 v0 = acc[ai][bj][m][0], v1 = acc[ai][bj][m][1];
;                         u32x4 w; w.x = pk2(v0[0] * __builtin_amdgcn_rcpf(bflo(a.x)), v0[1] * __builtin_amdgcn_rcpf(bfhi(a.x))); w.y = pk2(v0[2] * __builtin_amdgcn_rcpf(bflo(a.y)), v0[3] * __builtin_amdgcn_rcpf(bfhi(a.y)));
;                         w.z = pk2(v1[0] * __builtin_amdgcn_rcpf(bflo(a.z)), v1[1] * __builtin_amdgcn_rcpf(bfhi(a.z))); w.w = pk2(v1[2] * __builtin_amdgcn_rcpf(bflo(a.w)), v1[3] * __builtin_amdgcn_rcpf(bfhi(a.w)));
;                         *(u32x4*)(out + (size_t)(row0 + ai * HALF + m * 16) * DM + col0 + bj * HALF) = w;
;                     }
	v_lshlrev_b32_e32 v150, 16, v140
	v_and_b32_e32 v140, 0xffff0000, v140
	v_rcp_f32_e32 v150, v150
	v_rcp_f32_e32 v151, v140
	v_lshlrev_b32_e32 v140, 16, v141
	global_store_dwordx4 v[190:191], v[186:189], off
	v_ashrrev_i32_e32 v137, 31, v136
	v_lshlrev_b64 v[136:137], 12, v[136:137]
	v_rcp_f32_e32 v186, v140
	v_and_b32_e32 v140, 0xffff0000, v141
	v_rcp_f32_e32 v187, v140
	v_pk_mul_f32 v[140:141], v[100:101], v[150:151]
	v_lshl_add_u64 v[136:137], s[14:15], 0, v[136:137]
	v_cvt_pk_bf16_f32 v140, v140, v141
	v_lshlrev_b32_e32 v141, 16, v142
	v_pk_mul_f32 v[150:151], v[102:103], v[186:187]
	v_rcp_f32_e32 v186, v141
	v_and_b32_e32 v141, 0xffff0000, v142
	v_rcp_f32_e32 v187, v141
	v_lshlrev_b32_e32 v141, 16, v143
	v_rcp_f32_e32 v188, v141
	v_and_b32_e32 v141, 0xffff0000, v143
	v_rcp_f32_e32 v189, v141
	v_cvt_pk_bf16_f32 v141, v150, v151
	v_pk_mul_f32 v[142:143], v[96:97], v[186:187]
	global_store_dwordx4 v[148:149], v[144:147], off offset:256
	v_pk_mul_f32 v[150:151], v[98:99], v[188:189]
	v_cvt_pk_bf16_f32 v142, v142, v143
	v_cvt_pk_bf16_f32 v143, v150, v151
	v_lshl_add_u64 v[150:151], v[136:137], 0, v[152:153]
	v_pk_mul_f32 v[136:137], v[84:85], v[194:195]
	v_pk_mul_f32 v[144:145], v[86:87], v[196:197]
	v_cvt_pk_bf16_f32 v136, v136, v137
	v_lshlrev_b32_e32 v137, 16, v138
	v_rcp_f32_e32 v146, v137
	v_and_b32_e32 v137, 0xffff0000, v138
	v_rcp_f32_e32 v147, v137
	v_lshlrev_b32_e32 v137, 16, v139
	v_rcp_f32_e32 v186, v137
	v_and_b32_e32 v137, 0xffff0000, v139
	v_rcp_f32_e32 v187, v137
	v_cvt_pk_bf16_f32 v137, v144, v145
	v_pk_mul_f32 v[138:139], v[80:81], v[146:147]
	v_add_co_u32_e32 v152, vcc, s67, v176
	v_pk_mul_f32 v[144:145], v[82:83], v[186:187]
	v_cvt_pk_bf16_f32 v138, v138, v139
	v_cvt_pk_bf16_f32 v139, v144, v145
	v_lshlrev_b32_e32 v144, 16, v132
	v_and_b32_e32 v132, 0xffff0000, v132
	v_rcp_f32_e32 v144, v144
	v_rcp_f32_e32 v145, v132
	v_lshlrev_b32_e32 v132, 16, v133
	v_rcp_f32_e32 v146, v132
	v_and_b32_e32 v132, 0xffff0000, v133
	v_rcp_f32_e32 v147, v132
	v_pk_mul_f32 v[132:133], v[76:77], v[144:145]
	global_store_dwordx4 v[154:155], v[136:139], off offset:256
	v_cvt_pk_bf16_f32 v132, v132, v133
	v_lshlrev_b32_e32 v133, 16, v134
	v_rcp_f32_e32 v138, v133
	v_and_b32_e32 v133, 0xffff0000, v134
	v_rcp_f32_e32 v139, v133
	v_lshlrev_b32_e32 v133, 16, v135
	v_rcp_f32_e32 v144, v133
	v_and_b32_e32 v133, 0xffff0000, v135
	v_rcp_f32_e32 v145, v133
	v_pk_mul_f32 v[136:137], v[78:79], v[146:147]
	v_pk_mul_f32 v[134:135], v[72:73], v[138:139]
	v_cvt_pk_bf16_f32 v133, v136, v137
	v_pk_mul_f32 v[136:137], v[74:75], v[144:145]
	v_cvt_pk_bf16_f32 v134, v134, v135
	v_cvt_pk_bf16_f32 v135, v136, v137
	s_waitcnt vmcnt(5)
	v_lshlrev_b32_e32 v136, 16, v128
	v_and_b32_e32 v128, 0xffff0000, v128
	global_store_dwordx4 v[150:151], v[140:143], off
	v_addc_co_u32_e32 v153, vcc, 0, v177, vcc
	v_rcp_f32_e32 v136, v136
	v_rcp_f32_e32 v137, v128
	global_load_dwordx4 v[140:143], v[152:153], off
	v_lshlrev_b32_e32 v128, 16, v129
	v_rcp_f32_e32 v138, v128
	v_and_b32_e32 v128, 0xffff0000, v129
	v_rcp_f32_e32 v139, v128
	v_pk_mul_f32 v[128:129], v[68:69], v[136:137]
	global_store_dwordx4 v[190:191], v[132:135], off offset:256
	v_cvt_pk_bf16_f32 v128, v128, v129
	v_lshlrev_b32_e32 v129, 16, v130
	v_rcp_f32_e32 v134, v129
	v_and_b32_e32 v129, 0xffff0000, v130
	v_rcp_f32_e32 v135, v129
	v_lshlrev_b32_e32 v129, 16, v131
	v_rcp_f32_e32 v136, v129
	v_and_b32_e32 v129, 0xffff0000, v131
	v_rcp_f32_e32 v137, v129
	v_pk_mul_f32 v[132:133], v[70:71], v[138:139]
	v_pk_mul_f32 v[130:131], v[64:65], v[134:135]
	v_cvt_pk_bf16_f32 v129, v132, v133
	v_pk_mul_f32 v[132:133], v[66:67], v[136:137]
	v_cvt_pk_bf16_f32 v130, v130, v131
	v_cvt_pk_bf16_f32 v131, v132, v133
	global_store_dwordx4 v[150:151], v[128:131], off offset:256
	global_load_dwordx4 v[144:147], v[152:153], off offset:256
	s_nop 0
	v_add_co_u32_e32 v128, vcc, s68, v176
	s_nop 1
	v_addc_co_u32_e32 v129, vcc, 0, v177, vcc
	global_load_dwordx4 v[150:153], v[128:129], off
	v_add_co_u32_e32 v130, vcc, s69, v176
	s_nop 1
	v_addc_co_u32_e32 v131, vcc, 0, v177, vcc
	global_load_dwordx4 v[186:189], v[128:129], off offset:256
	global_load_dwordx4 v[190:193], v[130:131], off
	v_add_co_u32_e32 v128, vcc, s70, v176
	s_nop 1
	v_addc_co_u32_e32 v129, vcc, 0, v177, vcc
	global_load_dwordx4 v[136:139], v[130:131], off offset:256
	global_load_dwordx4 v[132:135], v[128:129], off
	s_waitcnt vmcnt(8)
	v_lshlrev_b32_e32 v130, 16, v140
	v_rcp_f32_e32 v154, v130
	v_and_b32_e32 v130, 0xffff0000, v140
	v_rcp_f32_e32 v155, v130
	v_lshlrev_b32_e32 v130, 16, v141
	v_rcp_f32_e32 v194, v130
	v_and_b32_e32 v130, 0xffff0000, v141
	v_rcp_f32_e32 v195, v130
	v_pk_mul_f32 v[140:141], v[60:61], v[154:155]
	global_load_dwordx4 v[128:131], v[128:129], off offset:256
	v_cvt_pk_bf16_f32 v140, v140, v141
	v_lshlrev_b32_e32 v141, 16, v142
	v_pk_mul_f32 v[154:155], v[62:63], v[194:195]
	v_rcp_f32_e32 v194, v141
	v_and_b32_e32 v141, 0xffff0000, v142
	v_rcp_f32_e32 v195, v141
	v_lshlrev_b32_e32 v141, 16, v143
	v_rcp_f32_e32 v196, v141
	v_and_b32_e32 v141, 0xffff0000, v143
	v_rcp_f32_e32 v197, v141
	v_cvt_pk_bf16_f32 v141, v154, v155
	v_pk_mul_f32 v[142:143], v[56:57], v[194:195]
	v_add_co_u32_e32 v194, vcc, s71, v148
	v_pk_mul_f32 v[154:155], v[58:59], v[196:197]
	s_waitcnt vmcnt(6)
; __device__ __forceinline__ unsigned pk2(float lo, float hi) { f32x2 v = {lo, hi}; bf16x2_t b = __builtin_convertvector(v, bf16x2_t); return __builtin_bit_cast(unsigned, b); }
; __device__ __forceinline__ float bflo(unsigned u) { return __uint_as_float(u << 16); }
; __device__ __forceinline__ float bfhi(unsigned u) { return __uint_as_float(u & 0xffff0000u); }
;     __device__ __forceinline__ void operator()(f32x4 (&acc)[2][2][4][2], const Unit& u, int wr, int wc, int fr, int fq) const {
;     ...
; #pragma unroll
;             for (int ai = 0; ai < 2; ++ai) {
;                 u32x4 gn[4][2];
; #pragma unroll
;                 for (int m = 0; m < 4; ++m)
; #pragma unroll
;                     for (int bj = 0; bj < 2; ++bj) gn[m][bj] = *(const u32x4*)(gz + (size_t)(ai * HALF + m * 16) * (3 * DM) + bj * HALF);
; #pragma unroll
;                 for (int m = 0; m < 4; ++m)
; #pragma unroll
;                     for (int bj = 0; bj < 2; ++bj) {
;                         const u32x4 a = gn[m][bj];
;                         const f32x4 v0 = acc[ai][bj][m][0], v1 = acc[ai][bj][m][1];
;                         u32x4 w; w.x = pk2(v0[0] * __builtin_amdgcn_rcpf(bflo(a.x)), v0[1] * __builtin_amdgcn_rcpf(bfhi(a.x))); w.y = pk2(v0[2] * __builtin_amdgcn_rcpf(bflo(a.y)), v0[3] * __builtin_amdgcn_rcpf(bfhi(a.y)));
;                         w.z = pk2(v1[0] * __builtin_amdgcn_rcpf(bflo(a.z)), v1[1] * __builtin_amdgcn_rcpf(bfhi(a.z))); w.w = pk2(v1[2] * __builtin_amdgcn_rcpf(bflo(a.w)), v1[3] * __builtin_amdgcn_rcpf(bfhi(a.w)));
;                         *(u32x4*)(out + (size_t)(row0 + ai * HALF + m * 16) * DM + col0 + bj * HALF) = w;
;                     }
	v_lshlrev_b32_e32 v196, 16, v144
	v_and_b32_e32 v144, 0xffff0000, v144
	v_rcp_f32_e32 v196, v196
	v_rcp_f32_e32 v197, v144
	v_lshlrev_b32_e32 v144, 16, v145
	v_and_b32_e32 v145, 0xffff0000, v145
	v_rcp_f32_e32 v144, v144
	v_rcp_f32_e32 v145, v145
	v_cvt_pk_bf16_f32 v142, v142, v143
	v_cvt_pk_bf16_f32 v143, v154, v155
	v_addc_co_u32_e32 v195, vcc, 0, v149, vcc
	global_store_dwordx4 v[194:195], v[140:143], off
	v_lshl_add_u64 v[154:155], v[148:149], 0, s[24:25]
	s_nop 0
	v_pk_mul_f32 v[140:141], v[28:29], v[196:197]
	v_pk_mul_f32 v[142:143], v[30:31], v[144:145]
	v_cvt_pk_bf16_f32 v140, v140, v141
	v_lshlrev_b32_e32 v141, 16, v146
	v_rcp_f32_e32 v144, v141
	v_and_b32_e32 v141, 0xffff0000, v146
	v_rcp_f32_e32 v145, v141
	v_lshlrev_b32_e32 v141, 16, v147
	v_rcp_f32_e32 v146, v141
	v_and_b32_e32 v141, 0xffff0000, v147
	v_rcp_f32_e32 v147, v141
	v_cvt_pk_bf16_f32 v141, v142, v143
	v_pk_mul_f32 v[142:143], v[24:25], v[144:145]
	v_pk_mul_f32 v[144:145], v[26:27], v[146:147]
	v_cvt_pk_bf16_f32 v142, v142, v143
	v_cvt_pk_bf16_f32 v143, v144, v145
	s_waitcnt vmcnt(6)
	v_lshlrev_b32_e32 v144, 16, v150
	v_and_b32_e32 v145, 0xffff0000, v150
	v_rcp_f32_e32 v144, v144
	v_rcp_f32_e32 v145, v145
	v_lshlrev_b32_e32 v146, 16, v151
	v_and_b32_e32 v147, 0xffff0000, v151
	v_rcp_f32_e32 v146, v146
	v_rcp_f32_e32 v147, v147
	global_store_dwordx4 v[154:155], v[140:143], off offset:256
	s_waitcnt vmcnt(6)
	v_lshlrev_b32_e32 v150, 16, v186
	v_and_b32_e32 v151, 0xffff0000, v186
	v_pk_mul_f32 v[140:141], v[52:53], v[144:145]
	v_pk_mul_f32 v[142:143], v[54:55], v[146:147]
	v_cvt_pk_bf16_f32 v140, v140, v141
	v_lshlrev_b32_e32 v141, 16, v152
	v_rcp_f32_e32 v144, v141
	v_and_b32_e32 v141, 0xffff0000, v152
	v_rcp_f32_e32 v145, v141
	v_lshlrev_b32_e32 v141, 16, v153
	v_rcp_f32_e32 v146, v141
	v_and_b32_e32 v141, 0xffff0000, v153
	v_rcp_f32_e32 v147, v141
	v_rcp_f32_e32 v150, v150
	v_rcp_f32_e32 v151, v151
	v_cvt_pk_bf16_f32 v141, v142, v143
	v_pk_mul_f32 v[142:143], v[48:49], v[144:145]
	v_pk_mul_f32 v[144:145], v[50:51], v[146:147]
	v_add_co_u32_e32 v146, vcc, s66, v148
	v_cvt_pk_bf16_f32 v142, v142, v143
	v_cvt_pk_bf16_f32 v143, v144, v145
	v_addc_co_u32_e32 v147, vcc, 0, v149, vcc
	global_store_dwordx4 v[146:147], v[140:143], off
	v_lshlrev_b32_e32 v152, 16, v187
	v_and_b32_e32 v153, 0xffff0000, v187
	v_pk_mul_f32 v[140:141], v[20:21], v[150:151]
	v_rcp_f32_e32 v152, v152
	v_cvt_pk_bf16_f32 v140, v140, v141
	v_lshlrev_b32_e32 v141, 16, v188
	v_rcp_f32_e32 v146, v141
	v_and_b32_e32 v141, 0xffff0000, v188
	v_rcp_f32_e32 v147, v141
	v_lshlrev_b32_e32 v141, 16, v189
	v_rcp_f32_e32 v153, v153
	v_rcp_f32_e32 v150, v141
	v_and_b32_e32 v141, 0xffff0000, v189
	v_rcp_f32_e32 v151, v141
	v_pk_mul_f32 v[142:143], v[22:23], v[152:153]
	v_lshl_add_u64 v[144:145], v[148:149], 0, s[26:27]
	v_cvt_pk_bf16_f32 v141, v142, v143
	v_pk_mul_f32 v[142:143], v[16:17], v[146:147]
	v_pk_mul_f32 v[146:147], v[18:19], v[150:151]
	v_cvt_pk_bf16_f32 v142, v142, v143
	v_cvt_pk_bf16_f32 v143, v146, v147
	s_waitcnt vmcnt(6)
	v_lshlrev_b32_e32 v146, 16, v190
	v_and_b32_e32 v147, 0xffff0000, v190
	v_rcp_f32_e32 v146, v146
	v_rcp_f32_e32 v147, v147
	v_lshlrev_b32_e32 v150, 16, v191
	v_and_b32_e32 v151, 0xffff0000, v191
	v_rcp_f32_e32 v150, v150
	v_rcp_f32_e32 v151, v151
	global_store_dwordx4 v[144:145], v[140:143], off offset:256
	s_nop 1
	v_pk_mul_f32 v[140:141], v[44:45], v[146:147]
	v_pk_mul_f32 v[142:143], v[46:47], v[150:151]
	v_cvt_pk_bf16_f32 v140, v140, v141
	v_lshlrev_b32_e32 v141, 16, v192
	v_rcp_f32_e32 v144, v141
	v_and_b32_e32 v141, 0xffff0000, v192
	v_rcp_f32_e32 v145, v141
	v_lshlrev_b32_e32 v141, 16, v193
	v_rcp_f32_e32 v146, v141
	v_and_b32_e32 v141, 0xffff0000, v193
	s_waitcnt vmcnt(6)
	v_lshlrev_b32_e32 v150, 16, v136
	v_and_b32_e32 v136, 0xffff0000, v136
	v_rcp_f32_e32 v147, v141
	v_rcp_f32_e32 v150, v150
	v_rcp_f32_e32 v151, v136
	v_lshlrev_b32_e32 v136, 16, v137
	v_rcp_f32_e32 v152, v136
	v_and_b32_e32 v136, 0xffff0000, v137
	v_cvt_pk_bf16_f32 v141, v142, v143
	v_pk_mul_f32 v[142:143], v[40:41], v[144:145]
	v_pk_mul_f32 v[144:145], v[42:43], v[146:147]
	v_add_co_u32_e32 v146, vcc, s72, v148
	v_rcp_f32_e32 v153, v136
	v_pk_mul_f32 v[136:137], v[12:13], v[150:151]
	v_cvt_pk_bf16_f32 v142, v142, v143
	v_cvt_pk_bf16_f32 v143, v144, v145
	v_addc_co_u32_e32 v147, vcc, 0, v149, vcc
	v_cvt_pk_bf16_f32 v136, v136, v137
	v_lshlrev_b32_e32 v137, 16, v138
	global_store_dwordx4 v[146:147], v[140:143], off
	v_lshl_add_u64 v[144:145], v[148:149], 0, s[28:29]
	s_nop 0
	v_rcp_f32_e32 v142, v137
	v_and_b32_e32 v137, 0xffff0000, v138
	v_rcp_f32_e32 v143, v137
	v_lshlrev_b32_e32 v137, 16, v139
	v_rcp_f32_e32 v146, v137
	v_and_b32_e32 v137, 0xffff0000, v139
	v_rcp_f32_e32 v147, v137
	v_pk_mul_f32 v[140:141], v[14:15], v[152:153]
	v_pk_mul_f32 v[138:139], v[8:9], v[142:143]
	v_cvt_pk_bf16_f32 v137, v140, v141
	v_pk_mul_f32 v[140:141], v[10:11], v[146:147]
	v_cvt_pk_bf16_f32 v138, v138, v139
	v_cvt_pk_bf16_f32 v139, v140, v141
	s_waitcnt vmcnt(6)
	v_lshlrev_b32_e32 v140, 16, v132
	v_and_b32_e32 v132, 0xffff0000, v132
	v_rcp_f32_e32 v140, v140
	v_rcp_f32_e32 v141, v132
	v_lshlrev_b32_e32 v132, 16, v133
	v_rcp_f32_e32 v142, v132
	v_and_b32_e32 v132, 0xffff0000, v133
	v_rcp_f32_e32 v143, v132
	v_pk_mul_f32 v[132:133], v[36:37], v[140:141]
	global_store_dwordx4 v[144:145], v[136:139], off offset:256
	v_cvt_pk_bf16_f32 v132, v132, v133
	v_lshlrev_b32_e32 v133, 16, v134
	v_rcp_f32_e32 v138, v133
	v_and_b32_e32 v133, 0xffff0000, v134
	v_rcp_f32_e32 v139, v133
	v_lshlrev_b32_e32 v133, 16, v135
	v_rcp_f32_e32 v140, v133
	v_and_b32_e32 v133, 0xffff0000, v135
	v_rcp_f32_e32 v141, v133
	v_pk_mul_f32 v[136:137], v[38:39], v[142:143]
	v_pk_mul_f32 v[134:135], v[32:33], v[138:139]
	v_cvt_pk_bf16_f32 v133, v136, v137
	v_pk_mul_f32 v[136:137], v[34:35], v[140:141]
	s_waitcnt vmcnt(6)
	v_lshlrev_b32_e32 v140, 16, v128
	v_and_b32_e32 v128, 0xffff0000, v128
	v_rcp_f32_e32 v140, v140
	v_rcp_f32_e32 v141, v128
	v_lshlrev_b32_e32 v128, 16, v129
	v_rcp_f32_e32 v142, v128
	v_and_b32_e32 v128, 0xffff0000, v129
	v_add_co_u32_e32 v138, vcc, s73, v148
	v_rcp_f32_e32 v143, v128
	v_pk_mul_f32 v[128:129], v[4:5], v[140:141]
	v_cvt_pk_bf16_f32 v134, v134, v135
	v_cvt_pk_bf16_f32 v135, v136, v137
	v_addc_co_u32_e32 v139, vcc, 0, v149, vcc
	v_cvt_pk_bf16_f32 v128, v128, v129
	v_lshlrev_b32_e32 v129, 16, v130
	global_store_dwordx4 v[138:139], v[132:135], off
	v_lshl_add_u64 v[136:137], v[148:149], 0, s[30:31]
	s_nop 0
	v_rcp_f32_e32 v134, v129
	v_and_b32_e32 v129, 0xffff0000, v130
	v_rcp_f32_e32 v135, v129
	v_lshlrev_b32_e32 v129, 16, v131
	v_rcp_f32_e32 v138, v129
	v_and_b32_e32 v129, 0xffff0000, v131
	v_rcp_f32_e32 v139, v129
	v_pk_mul_f32 v[132:133], v[6:7], v[142:143]
	v_pk_mul_f32 v[130:131], v[0:1], v[134:135]
	v_cvt_pk_bf16_f32 v129, v132, v133
	v_pk_mul_f32 v[132:133], v[2:3], v[138:139]
	v_cvt_pk_bf16_f32 v130, v130, v131
	v_cvt_pk_bf16_f32 v131, v132, v133
	global_store_dwordx4 v[136:137], v[128:131], off offset:256
	s_cbranch_execnz .LBB0_336
; __device__ __forceinline__ float bflo(unsigned u) { return __uint_as_float(u << 16); }
; __device__ __forceinline__ float bfhi(unsigned u) { return __uint_as_float(u & 0xffff0000u); }
;     __device__ __forceinline__ void operator()(f32x4 (&acc)[2][2][4][2], const Unit& u, int wr, int wc, int fr, int fq) const {
;     ...
;         if (z < 2) {
; #pragma unroll
;             for (int ai = 0; ai < 2; ++ai) {
;                 u32x4 gn[4][2], gd[4][2];
; #pragma unroll
;                 for (int m = 0; m < 4; ++m)
; #pragma unroll
;                     for (int bj = 0; bj < 2; ++bj) { const bf16_t* p = gz + (size_t)(ai * HALF + m * 16) * (3 * DM) + bj * HALF; gn[m][bj] = *(const u32x4*)p; gd[m][bj] = *(const u32x4*)(p + DM); }
; #pragma unroll
;                 for (int m = 0; m < 4; ++m)
; #pragma unroll
;                     for (int bj = 0; bj < 2; ++bj) {
;                         const u32x4 a = gn[m][bj], d = gd[m][bj];
;                         f32x4& v0 = acc[ai][bj][m][0]; f32x4& v1 = acc[ai][bj][m][1];
;                         v0[0] *= bflo(d.x) * __builtin_amdgcn_rcpf(bflo(a.x)); v0[1] *= bfhi(d.x) * __builtin_amdgcn_rcpf(bfhi(a.x));
;                         v0[2] *= bflo(d.y) * __builtin_amdgcn_rcpf(bflo(a.y)); v0[3] *= bfhi(d.y) * __builtin_amdgcn_rcpf(bfhi(a.y));
;                         v1[0] *= bflo(d.z) * __builtin_amdgcn_rcpf(bflo(a.z)); v1[1] *= bfhi(d.z) * __builtin_amdgcn_rcpf(bfhi(a.z));
;                         v1[2] *= bflo(d.w) * __builtin_amdgcn_rcpf(bflo(a.w)); v1[3] *= bfhi(d.w) * __builtin_amdgcn_rcpf(bfhi(a.w));
;                     }
.LBB0_338:
	s_nop 0
	v_add_co_u32_e32 v128, vcc, 0x1000, v176
	s_nop 0
	s_nop 0
	v_addc_co_u32_e32 v129, vcc, 0, v177, vcc
	global_load_dwordx4 v[186:189], v[128:129], off
	global_load_dwordx4 v[190:193], v[176:177], off offset:256
	global_load_dwordx4 v[194:197], v[128:129], off offset:256
	v_add_co_u32_e32 v128, vcc, s64, v176
	s_mov_b64 s[4:5], vcc
	v_add_co_u32_e32 v130, vcc, s74, v176
	s_nop 0
	s_nop 0
	v_addc_co_u32_e32 v131, vcc, 0, v177, vcc
	s_nop 0
	s_nop 0
	global_load_dwordx4 v[182:185], v[130:131], off offset:-4096
	global_load_dwordx4 v[202:205], v[130:131], off
	v_addc_co_u32_e64 v129, vcc, 0, v177, s[4:5]
	global_load_dwordx4 v[198:201], v[128:129], off offset:256
	v_add_co_u32_e32 v128, vcc, s65, v176
	s_nop 0
	s_nop 0
	v_addc_co_u32_e32 v129, vcc, 0, v177, vcc
	v_add_co_u32_e32 v132, vcc, s75, v176
	s_nop 0
	s_nop 0
	s_nop 0
	v_addc_co_u32_e32 v133, vcc, 0, v177, vcc
	global_load_dwordx4 v[206:209], v[130:131], off offset:256
	global_load_dwordx4 v[156:159], v[132:133], off offset:-4096
	global_load_dwordx4 v[152:155], v[132:133], off
	global_load_dwordx4 v[144:147], v[132:133], off offset:256
	v_add_co_u32_e32 v134, vcc, s66, v176
	s_waitcnt vmcnt(9)
	v_lshlrev_b32_e32 v234, 16, v230
	v_and_b32_e32 v235, 0xffff0000, v230
	v_lshlrev_b32_e32 v236, 16, v231
	v_and_b32_e32 v237, 0xffff0000, v231
	v_lshlrev_b32_e32 v238, 16, v232
	v_and_b32_e32 v239, 0xffff0000, v232
	v_lshlrev_b32_e32 v240, 16, v233
	v_and_b32_e32 v241, 0xffff0000, v233
	v_rcp_f32_e32 v210, v234
	v_rcp_f32_e32 v211, v235
	v_rcp_f32_e32 v212, v236
	v_rcp_f32_e32 v213, v237
	v_rcp_f32_e32 v214, v238
	v_rcp_f32_e32 v215, v239
	v_rcp_f32_e32 v218, v240
	v_rcp_f32_e32 v219, v241
	v_lshlrev_b32_e32 v220, 16, v186
	v_addc_co_u32_e32 v135, vcc, 0, v177, vcc
	v_add_co_u32_e32 v130, vcc, s76, v176
	v_and_b32_e32 v221, 0xffff0000, v186
	s_nop 0
	v_addc_co_u32_e32 v131, vcc, 0, v177, vcc
	global_load_dwordx4 v[148:151], v[128:129], off offset:256
	s_nop 0
	global_load_dwordx4 v[132:135], v[134:135], off offset:256
	s_nop 0
	global_load_dwordx4 v[140:143], v[130:131], off offset:-4096
	global_load_dwordx4 v[136:139], v[130:131], off
	s_nop 0
	global_load_dwordx4 v[128:131], v[130:131], off offset:256
	v_lshlrev_b32_e32 v186, 16, v187
	v_and_b32_e32 v187, 0xffff0000, v187
	s_waitcnt vmcnt(13)
	v_lshlrev_b32_e32 v216, 16, v190
	v_and_b32_e32 v226, 0xffff0000, v190
	v_pk_mul_f32 v[186:187], v[212:213], v[186:187]
	v_rcp_f32_e32 v212, v216
	v_rcp_f32_e32 v213, v226
	v_lshlrev_b32_e32 v222, 16, v188
	v_and_b32_e32 v223, 0xffff0000, v188
	s_waitcnt vmcnt(12)
	v_lshlrev_b32_e32 v224, 16, v194
	v_and_b32_e32 v225, 0xffff0000, v194
	v_lshlrev_b32_e32 v227, 16, v191
	v_and_b32_e32 v228, 0xffff0000, v191
	v_lshlrev_b32_e32 v190, 16, v195
	v_and_b32_e32 v191, 0xffff0000, v195
	v_pk_mul_f32 v[194:195], v[210:211], v[220:221]
	v_pk_mul_f32 v[210:211], v[214:215], v[222:223]
	v_rcp_f32_e32 v214, v227
	v_rcp_f32_e32 v215, v228
	v_pk_mul_f32 v[126:127], v[126:127], v[186:187]
	v_pk_mul_f32 v[186:187], v[212:213], v[224:225]
	v_lshlrev_b32_e32 v188, 16, v189
	v_pk_mul_f32 v[92:93], v[92:93], v[186:187]
	v_lshlrev_b32_e32 v186, 16, v192
	v_and_b32_e32 v187, 0xffff0000, v192
	v_and_b32_e32 v189, 0xffff0000, v189
	v_rcp_f32_e32 v186, v186
	v_rcp_f32_e32 v187, v187
	v_pk_mul_f32 v[188:189], v[218:219], v[188:189]
	v_pk_mul_f32 v[124:125], v[124:125], v[194:195]
	v_pk_mul_f32 v[122:123], v[122:123], v[188:189]
	v_pk_mul_f32 v[188:189], v[214:215], v[190:191]
	v_pk_mul_f32 v[120:121], v[120:121], v[210:211]
	v_pk_mul_f32 v[94:95], v[94:95], v[188:189]
	v_lshlrev_b32_e32 v188, 16, v196
	v_and_b32_e32 v189, 0xffff0000, v196
	v_pk_mul_f32 v[186:187], v[186:187], v[188:189]
	v_lshlrev_b32_e32 v188, 16, v193
	v_and_b32_e32 v189, 0xffff0000, v193
	v_rcp_f32_e32 v188, v188
	v_rcp_f32_e32 v189, v189
	v_pk_mul_f32 v[88:89], v[88:89], v[186:187]
	v_lshlrev_b32_e32 v186, 16, v197
	v_and_b32_e32 v187, 0xffff0000, v197
	v_pk_mul_f32 v[186:187], v[188:189], v[186:187]
	s_waitcnt vmcnt(11)
	v_lshlrev_b32_e32 v188, 16, v182
	v_and_b32_e32 v182, 0xffff0000, v182
	v_rcp_f32_e32 v188, v188
	v_rcp_f32_e32 v189, v182
	v_lshlrev_b32_e32 v182, 16, v183
	v_and_b32_e32 v183, 0xffff0000, v183
	v_rcp_f32_e32 v182, v182
	v_rcp_f32_e32 v183, v183
	v_pk_mul_f32 v[90:91], v[90:91], v[186:187]
	s_waitcnt vmcnt(10)
	v_lshlrev_b32_e32 v186, 16, v202
	v_and_b32_e32 v187, 0xffff0000, v202
	v_pk_mul_f32 v[186:187], v[188:189], v[186:187]
	s_nop 0
	v_pk_mul_f32 v[116:117], v[116:117], v[186:187]
	v_lshlrev_b32_e32 v186, 16, v203
	v_and_b32_e32 v187, 0xffff0000, v203
	v_pk_mul_f32 v[182:183], v[182:183], v[186:187]
	v_lshlrev_b32_e32 v186, 16, v184
	v_and_b32_e32 v184, 0xffff0000, v184
	v_rcp_f32_e32 v186, v186
	v_rcp_f32_e32 v187, v184
	v_lshlrev_b32_e32 v184, 16, v185
	v_and_b32_e32 v185, 0xffff0000, v185
	v_rcp_f32_e32 v184, v184
	v_rcp_f32_e32 v185, v185
	v_pk_mul_f32 v[118:119], v[118:119], v[182:183]
	v_lshlrev_b32_e32 v182, 16, v204
	v_and_b32_e32 v183, 0xffff0000, v204
	v_pk_mul_f32 v[182:183], v[186:187], v[182:183]
	s_nop 0
	v_pk_mul_f32 v[112:113], v[112:113], v[182:183]
	v_lshlrev_b32_e32 v182, 16, v205
	v_and_b32_e32 v183, 0xffff0000, v205
	v_pk_mul_f32 v[182:183], v[184:185], v[182:183]
	s_waitcnt vmcnt(9)
	v_lshlrev_b32_e32 v184, 16, v198
	v_and_b32_e32 v185, 0xffff0000, v198
	v_rcp_f32_e32 v184, v184
	v_rcp_f32_e32 v185, v185
	v_pk_mul_f32 v[114:115], v[114:115], v[182:183]
	s_waitcnt vmcnt(8)
; __device__ __forceinline__ float bflo(unsigned u) { return __uint_as_float(u << 16); }
; __device__ __forceinline__ float bfhi(unsigned u) { return __uint_as_float(u & 0xffff0000u); }
;     __device__ __forceinline__ void operator()(f32x4 (&acc)[2][2][4][2], const Unit& u, int wr, int wc, int fr, int fq) const {
;     ...
;         if (z < 2) {
; #pragma unroll
;             for (int ai = 0; ai < 2; ++ai) {
;                 u32x4 gn[4][2], gd[4][2];
; #pragma unroll
;                 for (int m = 0; m < 4; ++m)
; #pragma unroll
;                     for (int bj = 0; bj < 2; ++bj) { const bf16_t* p = gz + (size_t)(ai * HALF + m * 16) * (3 * DM) + bj * HALF; gn[m][bj] = *(const u32x4*)p; gd[m][bj] = *(const u32x4*)(p + DM); }
; #pragma unroll
;                 for (int m = 0; m < 4; ++m)
; #pragma unroll
;                     for (int bj = 0; bj < 2; ++bj) {
;                         const u32x4 a = gn[m][bj], d = gd[m][bj];
;                         f32x4& v0 = acc[ai][bj][m][0]; f32x4& v1 = acc[ai][bj][m][1];
;                         v0[0] *= bflo(d.x) * __builtin_amdgcn_rcpf(bflo(a.x)); v0[1] *= bfhi(d.x) * __builtin_amdgcn_rcpf(bfhi(a.x));
;                         v0[2] *= bflo(d.y) * __builtin_amdgcn_rcpf(bflo(a.y)); v0[3] *= bfhi(d.y) * __builtin_amdgcn_rcpf(bfhi(a.y));
;                         v1[0] *= bflo(d.z) * __builtin_amdgcn_rcpf(bflo(a.z)); v1[1] *= bfhi(d.z) * __builtin_amdgcn_rcpf(bfhi(a.z));
;                         v1[2] *= bflo(d.w) * __builtin_amdgcn_rcpf(bflo(a.w)); v1[3] *= bfhi(d.w) * __builtin_amdgcn_rcpf(bfhi(a.w));
;                     }
	v_lshlrev_b32_e32 v182, 16, v206
	v_and_b32_e32 v183, 0xffff0000, v206
	v_pk_mul_f32 v[182:183], v[184:185], v[182:183]
	v_lshlrev_b32_e32 v184, 16, v199
	v_and_b32_e32 v185, 0xffff0000, v199
	v_rcp_f32_e32 v184, v184
	v_rcp_f32_e32 v185, v185
	v_pk_mul_f32 v[84:85], v[84:85], v[182:183]
	v_lshlrev_b32_e32 v182, 16, v207
	v_and_b32_e32 v183, 0xffff0000, v207
	v_pk_mul_f32 v[182:183], v[184:185], v[182:183]
	v_lshlrev_b32_e32 v184, 16, v200
	v_and_b32_e32 v185, 0xffff0000, v200
	v_rcp_f32_e32 v184, v184
	v_rcp_f32_e32 v185, v185
	v_pk_mul_f32 v[86:87], v[86:87], v[182:183]
	v_lshlrev_b32_e32 v182, 16, v208
	v_and_b32_e32 v183, 0xffff0000, v208
	v_pk_mul_f32 v[182:183], v[184:185], v[182:183]
	v_lshlrev_b32_e32 v184, 16, v201
	v_and_b32_e32 v185, 0xffff0000, v201
	v_rcp_f32_e32 v184, v184
	v_rcp_f32_e32 v185, v185
	v_pk_mul_f32 v[80:81], v[80:81], v[182:183]
	v_lshlrev_b32_e32 v182, 16, v209
	v_and_b32_e32 v183, 0xffff0000, v209
	v_pk_mul_f32 v[182:183], v[184:185], v[182:183]
	s_waitcnt vmcnt(7)
	v_lshlrev_b32_e32 v184, 16, v156
	v_and_b32_e32 v156, 0xffff0000, v156
	v_pk_mul_f32 v[82:83], v[82:83], v[182:183]
	s_waitcnt vmcnt(6)
	v_lshlrev_b32_e32 v182, 16, v152
	v_and_b32_e32 v183, 0xffff0000, v152
	v_lshlrev_b32_e32 v152, 16, v157
	v_rcp_f32_e32 v185, v156
	v_rcp_f32_e32 v156, v152
	v_and_b32_e32 v152, 0xffff0000, v157
	v_rcp_f32_e32 v157, v152
	v_lshlrev_b32_e32 v152, 16, v153
	v_and_b32_e32 v153, 0xffff0000, v153
	v_rcp_f32_e32 v184, v184
	v_pk_mul_f32 v[152:153], v[156:157], v[152:153]
	v_lshlrev_b32_e32 v156, 16, v158
	v_and_b32_e32 v157, 0xffff0000, v158
	v_rcp_f32_e32 v156, v156
	v_rcp_f32_e32 v157, v157
	v_pk_mul_f32 v[110:111], v[110:111], v[152:153]
	v_lshlrev_b32_e32 v152, 16, v154
	v_and_b32_e32 v153, 0xffff0000, v154
	v_lshlrev_b32_e32 v154, 16, v159
	v_pk_mul_f32 v[152:153], v[156:157], v[152:153]
	v_rcp_f32_e32 v156, v154
	v_and_b32_e32 v154, 0xffff0000, v159
	v_rcp_f32_e32 v157, v154
	v_pk_mul_f32 v[104:105], v[104:105], v[152:153]
	v_lshlrev_b32_e32 v152, 16, v155
	v_and_b32_e32 v153, 0xffff0000, v155
	v_pk_mul_f32 v[152:153], v[156:157], v[152:153]
	s_waitcnt vmcnt(4)
	v_lshlrev_b32_e32 v154, 16, v148
	v_and_b32_e32 v148, 0xffff0000, v148
	v_pk_mul_f32 v[106:107], v[106:107], v[152:153]
	v_lshlrev_b32_e32 v152, 16, v144
	v_and_b32_e32 v153, 0xffff0000, v144
	v_lshlrev_b32_e32 v144, 16, v149
	v_rcp_f32_e32 v155, v148
	v_rcp_f32_e32 v148, v144
	v_and_b32_e32 v144, 0xffff0000, v149
	v_rcp_f32_e32 v149, v144
	v_lshlrev_b32_e32 v144, 16, v145
	v_and_b32_e32 v145, 0xffff0000, v145
	v_pk_mul_f32 v[182:183], v[184:185], v[182:183]
	v_pk_mul_f32 v[144:145], v[148:149], v[144:145]
	v_lshlrev_b32_e32 v148, 16, v150
	v_and_b32_e32 v149, 0xffff0000, v150
	v_rcp_f32_e32 v148, v148
	v_rcp_f32_e32 v149, v149
	v_pk_mul_f32 v[78:79], v[78:79], v[144:145]
	v_lshlrev_b32_e32 v144, 16, v146
	v_and_b32_e32 v145, 0xffff0000, v146
	v_lshlrev_b32_e32 v146, 16, v151
	v_pk_mul_f32 v[144:145], v[148:149], v[144:145]
	v_rcp_f32_e32 v148, v146
	v_and_b32_e32 v146, 0xffff0000, v151
	v_rcp_f32_e32 v149, v146
	v_pk_mul_f32 v[72:73], v[72:73], v[144:145]
	v_lshlrev_b32_e32 v144, 16, v147
	v_and_b32_e32 v145, 0xffff0000, v147
	v_pk_mul_f32 v[144:145], v[148:149], v[144:145]
	s_waitcnt vmcnt(2)
	v_lshlrev_b32_e32 v146, 16, v140
	v_and_b32_e32 v140, 0xffff0000, v140
	v_pk_mul_f32 v[74:75], v[74:75], v[144:145]
	s_waitcnt vmcnt(1)
	v_lshlrev_b32_e32 v144, 16, v136
	v_and_b32_e32 v145, 0xffff0000, v136
	v_lshlrev_b32_e32 v136, 16, v141
	v_rcp_f32_e32 v147, v140
	v_rcp_f32_e32 v140, v136
	v_and_b32_e32 v136, 0xffff0000, v141
	v_rcp_f32_e32 v141, v136
	v_lshlrev_b32_e32 v136, 16, v137
	v_and_b32_e32 v137, 0xffff0000, v137
	v_pk_mul_f32 v[108:109], v[108:109], v[182:183]
	v_pk_mul_f32 v[136:137], v[140:141], v[136:137]
	v_lshlrev_b32_e32 v140, 16, v142
	v_and_b32_e32 v141, 0xffff0000, v142
	v_rcp_f32_e32 v140, v140
	v_rcp_f32_e32 v141, v141
	v_pk_mul_f32 v[102:103], v[102:103], v[136:137]
	v_lshlrev_b32_e32 v136, 16, v138
	v_and_b32_e32 v137, 0xffff0000, v138
	v_lshlrev_b32_e32 v138, 16, v143
	v_add_co_u32_e32 v142, vcc, s77, v176
	v_pk_mul_f32 v[136:137], v[140:141], v[136:137]
	v_rcp_f32_e32 v140, v138
	v_and_b32_e32 v138, 0xffff0000, v143
	v_addc_co_u32_e32 v143, vcc, 0, v177, vcc
	global_load_dwordx4 v[182:185], v[142:143], off offset:-4096
	global_load_dwordx4 v[186:189], v[142:143], off
	global_load_dwordx4 v[194:197], v[142:143], off offset:256
	v_rcp_f32_e32 v141, v138
	v_lshlrev_b32_e32 v138, 16, v132
	v_and_b32_e32 v132, 0xffff0000, v132
	v_pk_mul_f32 v[96:97], v[96:97], v[136:137]
	v_lshlrev_b32_e32 v136, 16, v139
	v_and_b32_e32 v137, 0xffff0000, v139
	v_rcp_f32_e32 v138, v138
	v_rcp_f32_e32 v139, v132
	v_pk_mul_f32 v[136:137], v[140:141], v[136:137]
	v_rcp_f32_e32 v154, v154
	v_pk_mul_f32 v[98:99], v[98:99], v[136:137]
	s_waitcnt vmcnt(3)
; __device__ __forceinline__ float bflo(unsigned u) { return __uint_as_float(u << 16); }
; __device__ __forceinline__ float bfhi(unsigned u) { return __uint_as_float(u & 0xffff0000u); }
;     __device__ __forceinline__ void operator()(f32x4 (&acc)[2][2][4][2], const Unit& u, int wr, int wc, int fr, int fq) const {
;     ...
;         if (z < 2) {
; #pragma unroll
;             for (int ai = 0; ai < 2; ++ai) {
;                 u32x4 gn[4][2], gd[4][2];
; #pragma unroll
;                 for (int m = 0; m < 4; ++m)
; #pragma unroll
;                     for (int bj = 0; bj < 2; ++bj) { const bf16_t* p = gz + (size_t)(ai * HALF + m * 16) * (3 * DM) + bj * HALF; gn[m][bj] = *(const u32x4*)p; gd[m][bj] = *(const u32x4*)(p + DM); }
; #pragma unroll
;                 for (int m = 0; m < 4; ++m)
; #pragma unroll
;                     for (int bj = 0; bj < 2; ++bj) {
;                         const u32x4 a = gn[m][bj], d = gd[m][bj];
;                         f32x4& v0 = acc[ai][bj][m][0]; f32x4& v1 = acc[ai][bj][m][1];
;                         v0[0] *= bflo(d.x) * __builtin_amdgcn_rcpf(bflo(a.x)); v0[1] *= bfhi(d.x) * __builtin_amdgcn_rcpf(bfhi(a.x));
;                         v0[2] *= bflo(d.y) * __builtin_amdgcn_rcpf(bflo(a.y)); v0[3] *= bfhi(d.y) * __builtin_amdgcn_rcpf(bfhi(a.y));
;                         v1[0] *= bflo(d.z) * __builtin_amdgcn_rcpf(bflo(a.z)); v1[1] *= bfhi(d.z) * __builtin_amdgcn_rcpf(bfhi(a.z));
;                         v1[2] *= bflo(d.w) * __builtin_amdgcn_rcpf(bflo(a.w)); v1[3] *= bfhi(d.w) * __builtin_amdgcn_rcpf(bfhi(a.w));
;                     }
	v_lshlrev_b32_e32 v136, 16, v128
	v_and_b32_e32 v137, 0xffff0000, v128
	v_pk_mul_f32 v[136:137], v[138:139], v[136:137]
	v_lshlrev_b32_e32 v128, 16, v133
	v_pk_mul_f32 v[68:69], v[68:69], v[136:137]
	v_add_co_u32_e32 v136, vcc, s67, v176
	v_rcp_f32_e32 v132, v128
	s_nop 0
	v_addc_co_u32_e32 v137, vcc, 0, v177, vcc
	global_load_dwordx4 v[190:193], v[136:137], off offset:256
	v_and_b32_e32 v128, 0xffff0000, v133
	v_rcp_f32_e32 v133, v128
	v_lshlrev_b32_e32 v128, 16, v129
	v_and_b32_e32 v129, 0xffff0000, v129
	v_rcp_f32_e32 v146, v146
	v_pk_mul_f32 v[128:129], v[132:133], v[128:129]
	v_lshlrev_b32_e32 v132, 16, v130
	v_pk_mul_f32 v[70:71], v[70:71], v[128:129]
	v_lshlrev_b32_e32 v128, 16, v134
	v_and_b32_e32 v129, 0xffff0000, v134
	v_rcp_f32_e32 v128, v128
	v_rcp_f32_e32 v129, v129
	v_and_b32_e32 v133, 0xffff0000, v130
	v_lshlrev_b32_e32 v130, 16, v135
	v_pk_mul_f32 v[152:153], v[154:155], v[152:153]
	v_pk_mul_f32 v[128:129], v[128:129], v[132:133]
	v_rcp_f32_e32 v132, v130
	v_and_b32_e32 v130, 0xffff0000, v135
	v_rcp_f32_e32 v133, v130
	v_pk_mul_f32 v[64:65], v[64:65], v[128:129]
	v_lshlrev_b32_e32 v128, 16, v131
	v_and_b32_e32 v129, 0xffff0000, v131
	v_pk_mul_f32 v[128:129], v[132:133], v[128:129]
	v_pk_mul_f32 v[144:145], v[146:147], v[144:145]
	v_pk_mul_f32 v[66:67], v[66:67], v[128:129]
	v_add_co_u32_e32 v128, vcc, s68, v176
	v_pk_mul_f32 v[76:77], v[76:77], v[152:153]
	s_nop 0
	v_addc_co_u32_e32 v129, vcc, 0, v177, vcc
	v_add_co_u32_e32 v130, vcc, s78, v176
	v_pk_mul_f32 v[100:101], v[100:101], v[144:145]
	s_nop 0
	v_addc_co_u32_e32 v131, vcc, 0, v177, vcc
	global_load_dwordx4 v[198:201], v[130:131], off offset:-4096
	global_load_dwordx4 v[202:205], v[130:131], off
	global_load_dwordx4 v[206:209], v[128:129], off offset:256
	v_add_co_u32_e32 v128, vcc, s69, v176
	s_waitcnt vmcnt(6)
	v_lshlrev_b32_e32 v134, 16, v182
	v_addc_co_u32_e32 v129, vcc, 0, v177, vcc
	v_add_co_u32_e32 v132, vcc, s79, v176
	s_waitcnt vmcnt(5)
	v_lshlrev_b32_e32 v214, 16, v186
	v_addc_co_u32_e32 v133, vcc, 0, v177, vcc
	global_load_dwordx4 v[210:213], v[130:131], off offset:256
	global_load_dwordx4 v[156:159], v[132:133], off offset:-4096
	global_load_dwordx4 v[152:155], v[132:133], off
	global_load_dwordx4 v[144:147], v[132:133], off offset:256
	v_add_co_u32_e32 v130, vcc, s70, v176
	v_and_b32_e32 v215, 0xffff0000, v186
	s_nop 0
	v_addc_co_u32_e32 v131, vcc, 0, v177, vcc
	v_add_co_u32_e32 v132, vcc, s80, v176
	v_rcp_f32_e32 v176, v134
	v_and_b32_e32 v134, 0xffff0000, v182
	v_addc_co_u32_e32 v133, vcc, 0, v177, vcc
	v_rcp_f32_e32 v177, v134
	v_lshlrev_b32_e32 v182, 16, v183
	v_and_b32_e32 v183, 0xffff0000, v183
	v_rcp_f32_e32 v182, v182
	v_rcp_f32_e32 v183, v183
	v_pk_mul_f32 v[176:177], v[176:177], v[214:215]
	global_load_dwordx4 v[140:143], v[132:133], off offset:-4096
	global_load_dwordx4 v[136:139], v[132:133], off
	global_load_dwordx4 v[148:151], v[128:129], off offset:256
	s_nop 0
	global_load_dwordx4 v[128:131], v[130:131], off offset:256
	v_pk_mul_f32 v[60:61], v[60:61], v[176:177]
	v_lshlrev_b32_e32 v176, 16, v187
	v_and_b32_e32 v177, 0xffff0000, v187
	v_pk_mul_f32 v[176:177], v[182:183], v[176:177]
	v_lshlrev_b32_e32 v182, 16, v184
	v_and_b32_e32 v183, 0xffff0000, v184
	v_rcp_f32_e32 v182, v182
	v_rcp_f32_e32 v183, v183
	v_pk_mul_f32 v[62:63], v[62:63], v[176:177]
	v_lshlrev_b32_e32 v176, 16, v188
	v_and_b32_e32 v177, 0xffff0000, v188
	v_pk_mul_f32 v[176:177], v[182:183], v[176:177]
	v_lshlrev_b32_e32 v182, 16, v185
	v_and_b32_e32 v183, 0xffff0000, v185
	v_rcp_f32_e32 v182, v182
	v_rcp_f32_e32 v183, v183
	v_pk_mul_f32 v[56:57], v[56:57], v[176:177]
	v_lshlrev_b32_e32 v176, 16, v189
	v_and_b32_e32 v177, 0xffff0000, v189
	v_pk_mul_f32 v[176:177], v[182:183], v[176:177]
	s_waitcnt vmcnt(11)
	v_lshlrev_b32_e32 v182, 16, v190
	v_and_b32_e32 v183, 0xffff0000, v190
	v_rcp_f32_e32 v182, v182
	v_rcp_f32_e32 v183, v183
	v_pk_mul_f32 v[58:59], v[58:59], v[176:177]
	v_lshlrev_b32_e32 v176, 16, v194
	v_and_b32_e32 v177, 0xffff0000, v194
	v_pk_mul_f32 v[176:177], v[182:183], v[176:177]
	v_lshlrev_b32_e32 v182, 16, v191
	v_and_b32_e32 v183, 0xffff0000, v191
	v_rcp_f32_e32 v182, v182
	v_rcp_f32_e32 v183, v183
	v_pk_mul_f32 v[28:29], v[28:29], v[176:177]
	v_lshlrev_b32_e32 v176, 16, v195
	v_and_b32_e32 v177, 0xffff0000, v195
	v_pk_mul_f32 v[176:177], v[182:183], v[176:177]
	v_lshlrev_b32_e32 v182, 16, v192
	v_and_b32_e32 v183, 0xffff0000, v192
	v_rcp_f32_e32 v182, v182
	v_rcp_f32_e32 v183, v183
	v_pk_mul_f32 v[30:31], v[30:31], v[176:177]
	v_lshlrev_b32_e32 v176, 16, v196
	v_and_b32_e32 v177, 0xffff0000, v196
	v_pk_mul_f32 v[176:177], v[182:183], v[176:177]
	v_lshlrev_b32_e32 v182, 16, v193
	v_and_b32_e32 v183, 0xffff0000, v193
	v_rcp_f32_e32 v182, v182
	v_rcp_f32_e32 v183, v183
	v_pk_mul_f32 v[24:25], v[24:25], v[176:177]
	v_lshlrev_b32_e32 v176, 16, v197
	v_and_b32_e32 v177, 0xffff0000, v197
	v_pk_mul_f32 v[176:177], v[182:183], v[176:177]
	s_waitcnt vmcnt(10)
	v_lshlrev_b32_e32 v182, 16, v198
	v_and_b32_e32 v183, 0xffff0000, v198
	v_rcp_f32_e32 v182, v182
	v_rcp_f32_e32 v183, v183
	v_pk_mul_f32 v[26:27], v[26:27], v[176:177]
	s_waitcnt vmcnt(9)
; __device__ __forceinline__ float bflo(unsigned u) { return __uint_as_float(u << 16); }
; __device__ __forceinline__ float bfhi(unsigned u) { return __uint_as_float(u & 0xffff0000u); }
;     __device__ __forceinline__ void operator()(f32x4 (&acc)[2][2][4][2], const Unit& u, int wr, int wc, int fr, int fq) const {
;     ...
;         if (z < 2) {
; #pragma unroll
;             for (int ai = 0; ai < 2; ++ai) {
;                 u32x4 gn[4][2], gd[4][2];
; #pragma unroll
;                 for (int m = 0; m < 4; ++m)
; #pragma unroll
;                     for (int bj = 0; bj < 2; ++bj) { const bf16_t* p = gz + (size_t)(ai * HALF + m * 16) * (3 * DM) + bj * HALF; gn[m][bj] = *(const u32x4*)p; gd[m][bj] = *(const u32x4*)(p + DM); }
; #pragma unroll
;                 for (int m = 0; m < 4; ++m)
; #pragma unroll
;                     for (int bj = 0; bj < 2; ++bj) {
;                         const u32x4 a = gn[m][bj], d = gd[m][bj];
;                         f32x4& v0 = acc[ai][bj][m][0]; f32x4& v1 = acc[ai][bj][m][1];
;                         v0[0] *= bflo(d.x) * __builtin_amdgcn_rcpf(bflo(a.x)); v0[1] *= bfhi(d.x) * __builtin_amdgcn_rcpf(bfhi(a.x));
;                         v0[2] *= bflo(d.y) * __builtin_amdgcn_rcpf(bflo(a.y)); v0[3] *= bfhi(d.y) * __builtin_amdgcn_rcpf(bfhi(a.y));
;                         v1[0] *= bflo(d.z) * __builtin_amdgcn_rcpf(bflo(a.z)); v1[1] *= bfhi(d.z) * __builtin_amdgcn_rcpf(bfhi(a.z));
;                         v1[2] *= bflo(d.w) * __builtin_amdgcn_rcpf(bflo(a.w)); v1[3] *= bfhi(d.w) * __builtin_amdgcn_rcpf(bfhi(a.w));
;                     }
	v_lshlrev_b32_e32 v176, 16, v202
	v_and_b32_e32 v177, 0xffff0000, v202
	v_pk_mul_f32 v[176:177], v[182:183], v[176:177]
	v_lshlrev_b32_e32 v182, 16, v199
	v_and_b32_e32 v183, 0xffff0000, v199
	v_rcp_f32_e32 v182, v182
	v_rcp_f32_e32 v183, v183
	v_pk_mul_f32 v[52:53], v[52:53], v[176:177]
	v_lshlrev_b32_e32 v176, 16, v203
	v_and_b32_e32 v177, 0xffff0000, v203
	v_pk_mul_f32 v[176:177], v[182:183], v[176:177]
	v_lshlrev_b32_e32 v182, 16, v200
	v_and_b32_e32 v183, 0xffff0000, v200
	v_rcp_f32_e32 v182, v182
	v_rcp_f32_e32 v183, v183
	global_load_dwordx4 v[132:135], v[132:133], off offset:256
	v_pk_mul_f32 v[54:55], v[54:55], v[176:177]
	v_lshlrev_b32_e32 v176, 16, v204
	v_and_b32_e32 v177, 0xffff0000, v204
	v_pk_mul_f32 v[176:177], v[182:183], v[176:177]
	v_lshlrev_b32_e32 v182, 16, v201
	v_and_b32_e32 v183, 0xffff0000, v201
	v_rcp_f32_e32 v182, v182
	v_rcp_f32_e32 v183, v183
	v_pk_mul_f32 v[48:49], v[48:49], v[176:177]
	v_lshlrev_b32_e32 v176, 16, v205
	v_and_b32_e32 v177, 0xffff0000, v205
	v_pk_mul_f32 v[176:177], v[182:183], v[176:177]
	s_waitcnt vmcnt(9)
	v_lshlrev_b32_e32 v182, 16, v206
	v_and_b32_e32 v183, 0xffff0000, v206
	v_rcp_f32_e32 v182, v182
	v_rcp_f32_e32 v183, v183
	v_pk_mul_f32 v[50:51], v[50:51], v[176:177]
	s_waitcnt vmcnt(8)
	v_lshlrev_b32_e32 v176, 16, v210
	v_and_b32_e32 v177, 0xffff0000, v210
	v_pk_mul_f32 v[176:177], v[182:183], v[176:177]
	v_lshlrev_b32_e32 v182, 16, v207
	v_and_b32_e32 v183, 0xffff0000, v207
	v_rcp_f32_e32 v182, v182
	v_rcp_f32_e32 v183, v183
	v_pk_mul_f32 v[20:21], v[20:21], v[176:177]
	v_lshlrev_b32_e32 v176, 16, v211
	v_and_b32_e32 v177, 0xffff0000, v211
	v_pk_mul_f32 v[176:177], v[182:183], v[176:177]
	v_lshlrev_b32_e32 v182, 16, v208
	v_and_b32_e32 v183, 0xffff0000, v208
	v_rcp_f32_e32 v182, v182
	v_rcp_f32_e32 v183, v183
	v_pk_mul_f32 v[22:23], v[22:23], v[176:177]
	v_lshlrev_b32_e32 v176, 16, v212
	v_and_b32_e32 v177, 0xffff0000, v212
	v_pk_mul_f32 v[176:177], v[182:183], v[176:177]
	v_lshlrev_b32_e32 v182, 16, v209
	v_and_b32_e32 v183, 0xffff0000, v209
	v_rcp_f32_e32 v182, v182
	v_rcp_f32_e32 v183, v183
	v_pk_mul_f32 v[16:17], v[16:17], v[176:177]
	v_lshlrev_b32_e32 v176, 16, v213
	v_and_b32_e32 v177, 0xffff0000, v213
	v_pk_mul_f32 v[176:177], v[182:183], v[176:177]
	s_waitcnt vmcnt(7)
	v_lshlrev_b32_e32 v182, 16, v156
	v_and_b32_e32 v156, 0xffff0000, v156
	v_pk_mul_f32 v[18:19], v[18:19], v[176:177]
	s_waitcnt vmcnt(6)
	v_lshlrev_b32_e32 v176, 16, v152
	v_and_b32_e32 v177, 0xffff0000, v152
	v_lshlrev_b32_e32 v152, 16, v157
	v_rcp_f32_e32 v183, v156
	v_rcp_f32_e32 v156, v152
	v_and_b32_e32 v152, 0xffff0000, v157
	v_rcp_f32_e32 v157, v152
	v_lshlrev_b32_e32 v152, 16, v153
	v_and_b32_e32 v153, 0xffff0000, v153
	v_rcp_f32_e32 v182, v182
	v_pk_mul_f32 v[152:153], v[156:157], v[152:153]
	v_lshlrev_b32_e32 v156, 16, v158
	v_and_b32_e32 v157, 0xffff0000, v158
	v_rcp_f32_e32 v156, v156
	v_rcp_f32_e32 v157, v157
	v_pk_mul_f32 v[46:47], v[46:47], v[152:153]
	v_lshlrev_b32_e32 v152, 16, v154
	v_and_b32_e32 v153, 0xffff0000, v154
	v_lshlrev_b32_e32 v154, 16, v159
	v_pk_mul_f32 v[152:153], v[156:157], v[152:153]
	v_rcp_f32_e32 v156, v154
	v_and_b32_e32 v154, 0xffff0000, v159
	v_rcp_f32_e32 v157, v154
	v_pk_mul_f32 v[40:41], v[40:41], v[152:153]
	v_lshlrev_b32_e32 v152, 16, v155
	v_and_b32_e32 v153, 0xffff0000, v155
	v_pk_mul_f32 v[152:153], v[156:157], v[152:153]
	s_waitcnt vmcnt(2)
; __device__ __forceinline__ float bflo(unsigned u) { return __uint_as_float(u << 16); }
; __device__ __forceinline__ float bfhi(unsigned u) { return __uint_as_float(u & 0xffff0000u); }
;     __device__ __forceinline__ void operator()(f32x4 (&acc)[2][2][4][2], const Unit& u, int wr, int wc, int fr, int fq) const {
;     ...
;         if (z < 2) {
; #pragma unroll
;             for (int ai = 0; ai < 2; ++ai) {
;                 u32x4 gn[4][2], gd[4][2];
; #pragma unroll
;                 for (int m = 0; m < 4; ++m)
; #pragma unroll
;                     for (int bj = 0; bj < 2; ++bj) { const bf16_t* p = gz + (size_t)(ai * HALF + m * 16) * (3 * DM) + bj * HALF; gn[m][bj] = *(const u32x4*)p; gd[m][bj] = *(const u32x4*)(p + DM); }
; #pragma unroll
;                 for (int m = 0; m < 4; ++m)
; #pragma unroll
;                     for (int bj = 0; bj < 2; ++bj) {
;                         const u32x4 a = gn[m][bj], d = gd[m][bj];
;                         f32x4& v0 = acc[ai][bj][m][0]; f32x4& v1 = acc[ai][bj][m][1];
;                         v0[0] *= bflo(d.x) * __builtin_amdgcn_rcpf(bflo(a.x)); v0[1] *= bfhi(d.x) * __builtin_amdgcn_rcpf(bfhi(a.x));
;                         v0[2] *= bflo(d.y) * __builtin_amdgcn_rcpf(bflo(a.y)); v0[3] *= bfhi(d.y) * __builtin_amdgcn_rcpf(bfhi(a.y));
;                         v1[0] *= bflo(d.z) * __builtin_amdgcn_rcpf(bflo(a.z)); v1[1] *= bfhi(d.z) * __builtin_amdgcn_rcpf(bfhi(a.z));
;                         v1[2] *= bflo(d.w) * __builtin_amdgcn_rcpf(bflo(a.w)); v1[3] *= bfhi(d.w) * __builtin_amdgcn_rcpf(bfhi(a.w));
;                     }
	v_lshlrev_b32_e32 v154, 16, v148
	v_and_b32_e32 v148, 0xffff0000, v148
	v_pk_mul_f32 v[42:43], v[42:43], v[152:153]
	v_lshlrev_b32_e32 v152, 16, v144
	v_and_b32_e32 v153, 0xffff0000, v144
	v_lshlrev_b32_e32 v144, 16, v149
	v_rcp_f32_e32 v155, v148
	v_rcp_f32_e32 v148, v144
	v_and_b32_e32 v144, 0xffff0000, v149
	v_rcp_f32_e32 v149, v144
	v_lshlrev_b32_e32 v144, 16, v145
	v_and_b32_e32 v145, 0xffff0000, v145
	v_rcp_f32_e32 v154, v154
	v_pk_mul_f32 v[144:145], v[148:149], v[144:145]
	v_lshlrev_b32_e32 v148, 16, v150
	v_and_b32_e32 v149, 0xffff0000, v150
	v_rcp_f32_e32 v148, v148
	v_rcp_f32_e32 v149, v149
	v_pk_mul_f32 v[14:15], v[14:15], v[144:145]
	v_lshlrev_b32_e32 v144, 16, v146
	v_and_b32_e32 v145, 0xffff0000, v146
	v_lshlrev_b32_e32 v146, 16, v151
	v_pk_mul_f32 v[144:145], v[148:149], v[144:145]
	v_rcp_f32_e32 v148, v146
	v_and_b32_e32 v146, 0xffff0000, v151
	v_rcp_f32_e32 v149, v146
	v_pk_mul_f32 v[8:9], v[8:9], v[144:145]
	v_lshlrev_b32_e32 v144, 16, v147
	v_and_b32_e32 v145, 0xffff0000, v147
	v_pk_mul_f32 v[144:145], v[148:149], v[144:145]
	v_lshlrev_b32_e32 v146, 16, v140
	v_and_b32_e32 v140, 0xffff0000, v140
	v_pk_mul_f32 v[10:11], v[10:11], v[144:145]
	v_lshlrev_b32_e32 v144, 16, v136
	v_and_b32_e32 v145, 0xffff0000, v136
	v_lshlrev_b32_e32 v136, 16, v141
	v_rcp_f32_e32 v147, v140
	v_rcp_f32_e32 v140, v136
	v_and_b32_e32 v136, 0xffff0000, v141
	v_rcp_f32_e32 v141, v136
	v_lshlrev_b32_e32 v136, 16, v137
	v_and_b32_e32 v137, 0xffff0000, v137
	v_rcp_f32_e32 v146, v146
	v_pk_mul_f32 v[136:137], v[140:141], v[136:137]
	v_lshlrev_b32_e32 v140, 16, v142
	v_and_b32_e32 v141, 0xffff0000, v142
	v_rcp_f32_e32 v140, v140
	v_rcp_f32_e32 v141, v141
	v_pk_mul_f32 v[38:39], v[38:39], v[136:137]
	v_lshlrev_b32_e32 v136, 16, v138
	v_and_b32_e32 v137, 0xffff0000, v138
	v_lshlrev_b32_e32 v138, 16, v143
	v_pk_mul_f32 v[136:137], v[140:141], v[136:137]
	v_rcp_f32_e32 v140, v138
	v_and_b32_e32 v138, 0xffff0000, v143
	v_rcp_f32_e32 v141, v138
	s_waitcnt vmcnt(1)
	v_lshlrev_b32_e32 v138, 16, v128
	v_and_b32_e32 v128, 0xffff0000, v128
	v_pk_mul_f32 v[32:33], v[32:33], v[136:137]
	v_lshlrev_b32_e32 v136, 16, v139
	v_and_b32_e32 v137, 0xffff0000, v139
	v_rcp_f32_e32 v139, v128
	v_lshlrev_b32_e32 v128, 16, v129
	v_and_b32_e32 v129, 0xffff0000, v129
	v_rcp_f32_e32 v128, v128
	v_rcp_f32_e32 v129, v129
	v_pk_mul_f32 v[136:137], v[140:141], v[136:137]
	v_rcp_f32_e32 v138, v138
	v_pk_mul_f32 v[34:35], v[34:35], v[136:137]
	s_waitcnt vmcnt(0)
	v_lshlrev_b32_e32 v136, 16, v132
	v_and_b32_e32 v137, 0xffff0000, v132
	v_lshlrev_b32_e32 v132, 16, v133
	v_and_b32_e32 v133, 0xffff0000, v133
	v_pk_mul_f32 v[128:129], v[128:129], v[132:133]
	v_lshlrev_b32_e32 v132, 16, v130
	v_and_b32_e32 v130, 0xffff0000, v130
	v_rcp_f32_e32 v132, v132
	v_rcp_f32_e32 v133, v130
	v_lshlrev_b32_e32 v130, 16, v131
	v_and_b32_e32 v131, 0xffff0000, v131
	v_rcp_f32_e32 v130, v130
	v_rcp_f32_e32 v131, v131
	v_pk_mul_f32 v[6:7], v[6:7], v[128:129]
	v_lshlrev_b32_e32 v128, 16, v134
	v_and_b32_e32 v129, 0xffff0000, v134
	v_pk_mul_f32 v[128:129], v[132:133], v[128:129]
	v_pk_mul_f32 v[176:177], v[182:183], v[176:177]
	v_pk_mul_f32 v[0:1], v[0:1], v[128:129]
	v_lshlrev_b32_e32 v128, 16, v135
	v_and_b32_e32 v129, 0xffff0000, v135
	v_pk_mul_f32 v[152:153], v[154:155], v[152:153]
	v_pk_mul_f32 v[144:145], v[146:147], v[144:145]
	v_pk_mul_f32 v[136:137], v[138:139], v[136:137]
	v_pk_mul_f32 v[128:129], v[130:131], v[128:129]
	v_pk_mul_f32 v[44:45], v[44:45], v[176:177]
	v_pk_mul_f32 v[12:13], v[12:13], v[152:153]
	v_pk_mul_f32 v[36:37], v[36:37], v[144:145]
	v_pk_mul_f32 v[4:5], v[4:5], v[136:137]
	v_pk_mul_f32 v[2:3], v[2:3], v[128:129]
	s_andn2_b64 vcc, exec, s[2:3]
	s_mov_b64 s[2:3], -1
	s_cbranch_vccnz .LBB0_323

; #define LAS __attribute__((address_space(3)))
; #define MFMA32(a, b, c) __builtin_amdgcn_mfma_f32_32x32x16_bf16((a), (b), (c), 0, 0, 0)
; __device__ __forceinline__ void attn_item(const bf16_t* __restrict__ Q, const bf16_t* __restrict__ Kb, const bf16_t* __restrict__ VT, const bf16_t* __restrict__ GA, ...
;     ...
;     for (int j = jmin; j <= 8; ++j) {
;         const LAS unsigned char* kfp = pl + buf * ATT_WAVE_LDS + pr * ATP + 16 * hh;
;         const LAS unsigned char* vfp = pl + buf * ATT_WAVE_LDS + 64 * ATP + r * ATP + 16 * hh;
;         f32x16 s0, s1;
;         if (j <= 3) {
;             const bf16x8 k0 = *(const LAS bf16x8*)(kfp), k1 = *(const LAS bf16x8*)(kfp + 32 * ATP);
;             s0 = MFMA32(k0, qf[0], cinit); s1 = MFMA32(k1, qf[0], cinit);
;         } else {
;             const LAS float* bp = btab + (qloc + 64 * (8 - j) + 63 - 8 * hh);
; #pragma unroll
;             for (int i = 0; i < 16; ++i) {
;                 const int key = (i & 3) + 4 * ((i >> 2) & 1) + 16 * (i >> 3);
;                 s0[i] = bp[-key] - mref; s1[i] = bp[-key - 32] - mref;
;             }
;             const bf16x8 k0 = *(const LAS bf16x8*)(kfp), k1 = *(const LAS bf16x8*)(kfp + 32 * ATP);
;             s0 = MFMA32(k0, qf[0], s0); s1 = MFMA32(k1, qf[0], s1);
;         }
; #pragma unroll
;         for (int d0 = 1; d0 < 4; ++d0) {
;             const bf16x8 k0 = *(const LAS bf16x8*)(kfp + d0 * 32), k1 = *(const LAS bf16x8*)(kfp + 32 * ATP + d0 * 32);
;             s0 = MFMA32(k0, qf[d0], s0); s1 = MFMA32(k1, qf[d0], s1);
;         }
.LBB0_679:
	s_mul_i32 s7, s72, 0x4800
	s_add_i32 s28, s77, s7
	s_cmp_gt_i32 s84, 2
	v_add3_u32 v189, s28, v166, v167
	s_cbranch_scc0 .Latt1_nobias
	ds_read2_b32 v[50:51], v188 offset0:55 offset1:54
	ds_read2_b32 v[52:53], v188 offset0:53 offset1:52
	ds_read2_b32 v[54:55], v188 offset0:51 offset1:50
	ds_read2_b32 v[56:57], v188 offset0:49 offset1:48
	ds_read2_b32 v[58:59], v188 offset0:39 offset1:38
	ds_read2_b32 v[60:61], v188 offset0:37 offset1:36
	ds_read2_b32 v[62:63], v188 offset0:35 offset1:34
	ds_read2_b32 v[64:65], v188 offset0:33 offset1:32
	ds_read2_b32 v[66:67], v188 offset0:23 offset1:22
	ds_read2_b32 v[68:69], v188 offset0:21 offset1:20
	ds_read2_b32 v[70:71], v188 offset0:19 offset1:18
	ds_read2_b32 v[72:73], v188 offset0:17 offset1:16
	ds_read2_b32 v[74:75], v188 offset0:7 offset1:6
	ds_read2_b32 v[76:77], v188 offset0:5 offset1:4
	ds_read2_b32 v[78:79], v188 offset0:3 offset1:2
	ds_read2_b32 v[80:81], v188 offset0:1
	ds_read_b128 v[190:193], v189
	ds_read_b128 v[194:197], v189 offset:4608
	ds_read_b128 v[198:201], v189 offset:32
	ds_read_b128 v[202:205], v189 offset:4640
	ds_read_b128 v[206:209], v189 offset:64
	ds_read_b128 v[210:213], v189 offset:4672
	ds_read_b128 v[218:221], v189 offset:4704
	ds_read_b128 v[222:225], v189 offset:96
	s_waitcnt lgkmcnt(8)
	v_pk_add_f32 v[50:51], v[50:51], v[132:133] op_sel_hi:[1,0] neg_lo:[0,1] neg_hi:[0,1]
	v_pk_add_f32 v[52:53], v[52:53], v[132:133] op_sel_hi:[1,0] neg_lo:[0,1] neg_hi:[0,1]
	v_pk_add_f32 v[54:55], v[54:55], v[132:133] op_sel_hi:[1,0] neg_lo:[0,1] neg_hi:[0,1]
	v_pk_add_f32 v[56:57], v[56:57], v[132:133] op_sel_hi:[1,0] neg_lo:[0,1] neg_hi:[0,1]
	v_pk_add_f32 v[58:59], v[58:59], v[132:133] op_sel_hi:[1,0] neg_lo:[0,1] neg_hi:[0,1]
	v_pk_add_f32 v[60:61], v[60:61], v[132:133] op_sel_hi:[1,0] neg_lo:[0,1] neg_hi:[0,1]
	v_pk_add_f32 v[62:63], v[62:63], v[132:133] op_sel_hi:[1,0] neg_lo:[0,1] neg_hi:[0,1]
	v_pk_add_f32 v[64:65], v[64:65], v[132:133] op_sel_hi:[1,0] neg_lo:[0,1] neg_hi:[0,1]
	v_pk_add_f32 v[66:67], v[66:67], v[132:133] op_sel_hi:[1,0] neg_lo:[0,1] neg_hi:[0,1]
	v_pk_add_f32 v[68:69], v[68:69], v[132:133] op_sel_hi:[1,0] neg_lo:[0,1] neg_hi:[0,1]
	v_pk_add_f32 v[70:71], v[70:71], v[132:133] op_sel_hi:[1,0] neg_lo:[0,1] neg_hi:[0,1]
	v_pk_add_f32 v[72:73], v[72:73], v[132:133] op_sel_hi:[1,0] neg_lo:[0,1] neg_hi:[0,1]
	v_pk_add_f32 v[74:75], v[74:75], v[132:133] op_sel_hi:[1,0] neg_lo:[0,1] neg_hi:[0,1]
	v_pk_add_f32 v[76:77], v[76:77], v[132:133] op_sel_hi:[1,0] neg_lo:[0,1] neg_hi:[0,1]
	v_pk_add_f32 v[78:79], v[78:79], v[132:133] op_sel_hi:[1,0] neg_lo:[0,1] neg_hi:[0,1]
	v_pk_add_f32 v[80:81], v[80:81], v[132:133] op_sel_hi:[1,0] neg_lo:[0,1] neg_hi:[0,1]
	s_waitcnt lgkmcnt(7)
	v_mfma_f32_32x32x16_bf16 v[50:65], v[190:193], v[82:85], v[50:65]
	s_waitcnt lgkmcnt(6)
	v_mfma_f32_32x32x16_bf16 v[66:81], v[194:197], v[82:85], v[66:81]
	s_branch .Latt1_qkrest

; #define LAS __attribute__((address_space(3)))
; #define MFMA32(a, b, c) __builtin_amdgcn_mfma_f32_32x32x16_bf16((a), (b), (c), 0, 0, 0)
; __device__ __forceinline__ void attn_item(const bf16_t* __restrict__ Q, const bf16_t* __restrict__ Kb, const bf16_t* __restrict__ VT, const bf16_t* __restrict__ GA, ...
;     ...
;         for (int d0 = 1; d0 < 4; ++d0) {
;             const bf16x8 k0 = *(const LAS bf16x8*)(kfp + d0 * 32), k1 = *(const LAS bf16x8*)(kfp + 32 * ATP + d0 * 32);
;             s0 = MFMA32(k0, qf[d0], s0); s1 = MFMA32(k1, qf[d0], s1);
;         }
;         float tmax = fmaxf(s0[0], s1[0]);
; #pragma unroll
;         for (int i = 1; i < 16; ++i) tmax = fmaxf(tmax, fmaxf(s0[i], s1[i]));
;         tmax = fmaxf(tmax, __shfl_xor(tmax, 32));
;         if (j == jmin || __any(tmax > ATT_THR)) {
;             const float dl = (j == jmin) ? tmax : fmaxf(tmax, 0.f);
;             mref += dl;
;             const float alpha = (j == jmin) ? 1.f : __builtin_amdgcn_exp2f(-dl);
;             lrun *= alpha;
; #pragma unroll
;             for (int i = 0; i < 16; ++i) { s0[i] -= dl; s1[i] -= dl; o0[i] *= alpha; o1[i] *= alpha; cinit[i] = cfar - mref; }
.Latt1_qkrest:
	s_waitcnt lgkmcnt(5)
	v_mfma_f32_32x32x16_bf16 v[50:65], v[198:201], v[86:89], v[50:65]
	s_waitcnt lgkmcnt(4)
	v_mfma_f32_32x32x16_bf16 v[66:81], v[202:205], v[86:89], v[66:81]
	s_waitcnt lgkmcnt(3)
	v_mfma_f32_32x32x16_bf16 v[50:65], v[206:209], v[90:93], v[50:65]
	s_waitcnt lgkmcnt(2)
	v_mfma_f32_32x32x16_bf16 v[66:81], v[210:213], v[90:93], v[66:81]
	s_waitcnt lgkmcnt(1)
	v_mfma_f32_32x32x16_bf16 v[66:81], v[218:221], v[94:97], v[66:81]
	s_waitcnt lgkmcnt(0)
	v_mfma_f32_32x32x16_bf16 v[50:65], v[222:225], v[94:97], v[50:65]
	s_nop 9
	v_max_f32_e32 v189, v67, v67
	s_nop 1
	v_max_f32_e32 v190, v51, v51
	v_max_f32_e32 v189, v190, v189
	v_max_f32_e32 v190, v68, v68
	v_max_f32_e32 v191, v52, v52
	v_max_f32_e32 v190, v191, v190
	v_max_f32_e32 v191, v69, v69
	v_max_f32_e32 v192, v53, v53
	v_max3_f32 v189, v50, v66, v189
	v_max_f32_e32 v191, v192, v191
	v_max3_f32 v189, v189, v190, v191
	v_max_f32_e32 v190, v70, v70
	v_max_f32_e32 v191, v54, v54
	v_max_f32_e32 v190, v191, v190
	v_max_f32_e32 v191, v71, v71
	v_max_f32_e32 v192, v55, v55
	v_max_f32_e32 v191, v192, v191
	v_max3_f32 v189, v189, v190, v191
	v_max_f32_e32 v190, v72, v72
	v_max_f32_e32 v191, v56, v56
	v_max_f32_e32 v190, v191, v190
	v_max_f32_e32 v191, v73, v73
	v_max_f32_e32 v192, v57, v57
	v_max_f32_e32 v191, v192, v191
	v_max3_f32 v189, v189, v190, v191
	v_max_f32_e32 v190, v74, v74
	v_max_f32_e32 v191, v58, v58
	v_max_f32_e32 v190, v191, v190
	v_max_f32_e32 v191, v75, v75
	v_max_f32_e32 v192, v59, v59
	v_max_f32_e32 v191, v192, v191
	v_max3_f32 v189, v189, v190, v191
	v_max_f32_e32 v190, v76, v76
	v_max_f32_e32 v191, v60, v60
	v_max_f32_e32 v190, v191, v190
	v_max_f32_e32 v191, v77, v77
	v_max_f32_e32 v192, v61, v61
	v_max_f32_e32 v191, v192, v191
	v_max3_f32 v189, v189, v190, v191
	v_max_f32_e32 v190, v78, v78
	v_max_f32_e32 v191, v62, v62
	v_max_f32_e32 v190, v191, v190
	v_max_f32_e32 v191, v79, v79
	v_max_f32_e32 v192, v63, v63
	v_max_f32_e32 v191, v192, v191
	v_max3_f32 v189, v189, v190, v191
	v_max_f32_e32 v190, v80, v80
	v_max_f32_e32 v191, v64, v64
	v_max_f32_e32 v190, v191, v190
	v_max_f32_e32 v191, v81, v81
	v_max_f32_e32 v192, v65, v65
	v_max_f32_e32 v191, v192, v191
	v_max3_f32 v189, v189, v190, v191
	ds_bpermute_b32 v190, v1, v189
	s_waitcnt lgkmcnt(0)
	v_max_f32_e32 v190, v190, v190
	v_max_f32_e32 v189, v189, v190
	v_cmp_lt_f32_e32 vcc, s33, v189
	s_cbranch_vccz .LBB0_685
	v_max_f32_e32 v34, v189, v189
	v_max_f32_e32 v36, 0, v34
	v_exp_f32_e64 v38, -v36
	v_add_f32_e32 v132, v132, v36
	v_sub_f32_e32 v34, v0, v132
	v_pk_add_f32 v[50:51], v[50:51], v[36:37] op_sel_hi:[1,0] neg_lo:[0,1] neg_hi:[0,1]
	v_pk_add_f32 v[66:67], v[66:67], v[36:37] op_sel_hi:[1,0] neg_lo:[0,1] neg_hi:[0,1]
	v_pk_add_f32 v[52:53], v[52:53], v[36:37] op_sel_hi:[1,0] neg_lo:[0,1] neg_hi:[0,1]
	v_pk_add_f32 v[68:69], v[68:69], v[36:37] op_sel_hi:[1,0] neg_lo:[0,1] neg_hi:[0,1]
	v_pk_add_f32 v[54:55], v[54:55], v[36:37] op_sel_hi:[1,0] neg_lo:[0,1] neg_hi:[0,1]
	v_pk_add_f32 v[70:71], v[70:71], v[36:37] op_sel_hi:[1,0] neg_lo:[0,1] neg_hi:[0,1]
	v_pk_add_f32 v[56:57], v[56:57], v[36:37] op_sel_hi:[1,0] neg_lo:[0,1] neg_hi:[0,1]
	v_pk_add_f32 v[72:73], v[72:73], v[36:37] op_sel_hi:[1,0] neg_lo:[0,1] neg_hi:[0,1]
	v_pk_add_f32 v[58:59], v[58:59], v[36:37] op_sel_hi:[1,0] neg_lo:[0,1] neg_hi:[0,1]
	v_pk_add_f32 v[74:75], v[74:75], v[36:37] op_sel_hi:[1,0] neg_lo:[0,1] neg_hi:[0,1]
	v_pk_add_f32 v[60:61], v[60:61], v[36:37] op_sel_hi:[1,0] neg_lo:[0,1] neg_hi:[0,1]
	v_pk_add_f32 v[76:77], v[76:77], v[36:37] op_sel_hi:[1,0] neg_lo:[0,1] neg_hi:[0,1]
	v_pk_add_f32 v[62:63], v[62:63], v[36:37] op_sel_hi:[1,0] neg_lo:[0,1] neg_hi:[0,1]
	v_pk_add_f32 v[78:79], v[78:79], v[36:37] op_sel_hi:[1,0] neg_lo:[0,1] neg_hi:[0,1]
	v_pk_add_f32 v[64:65], v[64:65], v[36:37] op_sel_hi:[1,0] neg_lo:[0,1] neg_hi:[0,1]
	v_pk_add_f32 v[80:81], v[80:81], v[36:37] op_sel_hi:[1,0] neg_lo:[0,1] neg_hi:[0,1]
	v_pk_mul_f32 v[16:17], v[16:17], v[38:39] op_sel_hi:[1,0]
	v_pk_mul_f32 v[14:15], v[14:15], v[38:39] op_sel_hi:[1,0]
	v_pk_mul_f32 v[12:13], v[12:13], v[38:39] op_sel_hi:[1,0]
	v_pk_mul_f32 v[10:11], v[10:11], v[38:39] op_sel_hi:[1,0]
	v_pk_mul_f32 v[8:9], v[8:9], v[38:39] op_sel_hi:[1,0]
	v_pk_mul_f32 v[6:7], v[6:7], v[38:39] op_sel_hi:[1,0]
	v_pk_mul_f32 v[4:5], v[4:5], v[38:39] op_sel_hi:[1,0]
	v_pk_mul_f32 v[2:3], v[2:3], v[38:39] op_sel_hi:[1,0]
	v_pk_mul_f32 v[32:33], v[32:33], v[38:39] op_sel_hi:[1,0]
	v_pk_mul_f32 v[30:31], v[30:31], v[38:39] op_sel_hi:[1,0]
	v_pk_mul_f32 v[28:29], v[28:29], v[38:39] op_sel_hi:[1,0]
	v_pk_mul_f32 v[26:27], v[26:27], v[38:39] op_sel_hi:[1,0]
	v_pk_mul_f32 v[24:25], v[24:25], v[38:39] op_sel_hi:[1,0]
	v_pk_mul_f32 v[22:23], v[22:23], v[38:39] op_sel_hi:[1,0]
	v_pk_mul_f32 v[20:21], v[20:21], v[38:39] op_sel_hi:[1,0]
	v_pk_mul_f32 v[18:19], v[18:19], v[38:39] op_sel_hi:[1,0]
	v_mul_f32_e32 v187, v187, v38
	v_mov_b32_e32 v35, v34
	v_mov_b32_e32 v36, v34
	v_mov_b32_e32 v37, v34
	v_mov_b32_e32 v38, v34
	v_mov_b32_e32 v39, v34
	v_mov_b32_e32 v40, v34
	v_mov_b32_e32 v41, v34
	v_mov_b32_e32 v42, v34
	v_mov_b32_e32 v43, v34
	v_mov_b32_e32 v44, v34
	v_mov_b32_e32 v45, v34
	v_mov_b32_e32 v46, v34
	v_mov_b32_e32 v47, v34
	v_mov_b32_e32 v48, v34
	v_mov_b32_e32 v49, v34
